# peel first K-tile iteration of all six GEMM loops with MFMA SrcC=0, removing the 128-register accumulator zero-init per tile; plus scalarized packed-f32 VALU
# speedup vs baseline: 1.0143x; 1.0046x over previous
; #define PG8_STAGE(bufoff, gbase, voff) do { _Pragma("unroll") for (int _i = 0; _i < 2; ++_i) \
;         __builtin_amdgcn_global_load_lds((const unsigned*)((const char*)(gbase) + (voff)[_i]), (LAS unsigned*)(lds + (bufoff) + ldsw + _i * 8192), 16, 0, 0); } while (0)
; #define PG8_LDA(dst, b, h) do { _Pragma("unroll") for (int m = 0; m < 4; ++m) _Pragma("unroll") for (int k = 0; k < 2; ++k) dst[m][k] = *(const LAS bf16x8*)(lds + PG8_SA(b, h) + aoff + m * 2048 + k * 1024); } while (0)
; #define PG8_LDB(dst, b, h) do { _Pragma("unroll") for (int n = 0; n < 2; ++n) _Pragma("unroll") for (int k = 0; k < 2; ++k) dst[n][k] = *(const LAS bf16x8*)(lds + PG8_SB(b, h) + boff + n * 2048 + k * 1024); } while (0)
; #define PG8_MMA(ai, bj, At, Bt) do { __builtin_amdgcn_s_setprio(1); _Pragma("unroll") for (int m = 0; m < 4; ++m) _Pragma("unroll") for (int n = 0; n < 2; ++n) _Pragma("unroll") for (int k = 0; k < 2; ++k) \
;         acc[ai][bj][m][n] = __builtin_amdgcn_mfma_f32_16x16x32_bf16(Bt[n][k], At[m][k], acc[ai][bj][m][n], 0, 0, 0); __builtin_amdgcn_s_setprio(0); } while (0)
; template <class Epi, class Sched, bool ALIGN_EPI = true, bool SP2 = true>
; __device__ __forceinline__ void gemm_phase(LAS unsigned char* lds, const int K, const Sched& S, const Epi& E) {
;     ...
;     f32x4 acc[2][2][4][2];
; #pragma unroll
;     for (int a = 0; a < 2; ++a)
; #pragma unroll
;         for (int b = 0; b < 2; ++b)
; #pragma unroll
;             for (int m = 0; m < 4; ++m)
; #pragma unroll
;                 for (int n = 0; n < 2; ++n) acc[a][b][m][n] = (f32x4){0.f, 0.f, 0.f, 0.f};
;     ...
;         for (int t = 0; t < nt; t += 2) {
;             const bool last = (t == nt - 2);
;             const char* a1 = cA + (size_t)(t + 1) * kstep;
;             const char* a2 = last ? nA : cA + (size_t)(t + 2) * kstep; const char* b2 = last ? nB : cB + (size_t)(t + 2) * kstep;
;             const char* a3 = a2 + kstep; const char* b3 = b2 + kstep;
;             if constexpr (SP2) {
;             PG8_LDB(B0, 0, 0); PG8_LDB(B1, 0, 1); PG8_SCHED; PG8_LDA(At, 0, 0); PG8_STAGE(PG8_SA(1, 1), a1 + hstep, voffA);
;             PG8_WAIT_V(8); PG8_WAIT_L(0); PG8_BAR; PG8_MMA(0, 0, At, B0); PG8_MMA(0, 1, At, B1); PG8_BAR; PG8_SCHED;
;             PG8_LDA(At, 0, 1); PG8_STAGE(PG8_SB(0, 0), b2, voffB); PG8_STAGE(PG8_SB(0, 1), b2 + hstep, voffB); PG8_STAGE(PG8_SA(0, 0), a2, voffA);
.LBB0_175:
	s_add_u32 s18, s18, 0x40080
	s_addc_u32 s19, s19, 0
	s_add_u32 s11, s36, 0x100
	s_addc_u32 s13, s37, 0
	s_mov_b32 s68, -2
	s_add_u32 s36, s18, 0xfffc0080
	s_addc_u32 s37, s19, -1
	s_add_i32 s69, 0, 0x10000
	s_cmp_eq_u32 s68, 12
	s_cselect_b32 s39, s15, s37
	s_cselect_b32 s38, s14, s36
	s_cselect_b32 s37, s17, s13
	s_cselect_b32 s36, s16, s11
	s_add_i32 s72, 0, 0x14000
	v_add_u32_e32 v154, s69, v144
	v_add_u32_e32 v170, s72, v144
	ds_read_b128 v[138:141], v154
	ds_read_b128 v[146:149], v154 offset:1024
	ds_read_b128 v[150:153], v154 offset:2048
	ds_read_b128 v[154:157], v154 offset:3072
	ds_read_b128 v[158:161], v170
	ds_read_b128 v[162:165], v170 offset:1024
	ds_read_b128 v[166:169], v170 offset:2048
	ds_read_b128 v[170:173], v170 offset:3072
	v_lshl_add_u64 v[190:191], s[18:19], 0, v[134:135]
	s_add_i32 m0, s40, 0xc000
	ds_read_b128 v[174:177], v145
	ds_read_b128 v[178:181], v145 offset:1024
	ds_read_b128 v[182:185], v145 offset:2048
	ds_read_b128 v[186:189], v145 offset:3072
	ds_read_b128 v[208:211], v145 offset:4096
	ds_read_b128 v[212:215], v145 offset:5120
	ds_read_b128 v[216:219], v145 offset:6144
	ds_read_b128 v[220:223], v145 offset:7168
	global_load_lds_dwordx4 v[190:191], off
	v_lshl_add_u64 v[190:191], s[18:19], 0, v[136:137]
	s_add_i32 m0, s40, 0xe000
	s_nop 0
	global_load_lds_dwordx4 v[190:191], off
	s_waitcnt vmcnt(8)
	s_waitcnt lgkmcnt(0)
	s_barrier
	s_setprio 1
	s_waitcnt lgkmcnt(0)
	v_mfma_f32_16x16x32_bf16 v[124:127], v[138:141], v[174:177], 0
	v_mfma_f32_16x16x32_bf16 v[116:119], v[150:153], v[174:177], 0
	v_mfma_f32_16x16x32_bf16 v[108:111], v[138:141], v[182:185], 0
	v_mfma_f32_16x16x32_bf16 v[100:103], v[150:153], v[182:185], 0
	v_mfma_f32_16x16x32_bf16 v[92:95], v[138:141], v[208:211], 0
	v_mfma_f32_16x16x32_bf16 v[84:87], v[150:153], v[208:211], 0
	v_mfma_f32_16x16x32_bf16 v[76:79], v[138:141], v[216:219], 0
	v_mfma_f32_16x16x32_bf16 v[68:71], v[150:153], v[216:219], 0
	v_mfma_f32_16x16x32_bf16 v[124:127], v[146:149], v[178:181], v[124:127]
	v_mfma_f32_16x16x32_bf16 v[116:119], v[154:157], v[178:181], v[116:119]
	v_mfma_f32_16x16x32_bf16 v[108:111], v[146:149], v[186:189], v[108:111]
	v_mfma_f32_16x16x32_bf16 v[100:103], v[154:157], v[186:189], v[100:103]
	v_mfma_f32_16x16x32_bf16 v[92:95], v[146:149], v[212:215], v[92:95]
	v_mfma_f32_16x16x32_bf16 v[84:87], v[154:157], v[212:215], v[84:87]
	v_mfma_f32_16x16x32_bf16 v[76:79], v[146:149], v[220:223], v[76:79]
	v_mfma_f32_16x16x32_bf16 v[68:71], v[154:157], v[220:223], v[68:71]
	s_setprio 0
	s_setprio 1
	v_mfma_f32_16x16x32_bf16 v[120:123], v[158:161], v[174:177], 0
	v_mfma_f32_16x16x32_bf16 v[112:115], v[166:169], v[174:177], 0
	v_mfma_f32_16x16x32_bf16 v[104:107], v[158:161], v[182:185], 0
	v_mfma_f32_16x16x32_bf16 v[96:99], v[166:169], v[182:185], 0
	v_mfma_f32_16x16x32_bf16 v[88:91], v[158:161], v[208:211], 0
	v_mfma_f32_16x16x32_bf16 v[80:83], v[166:169], v[208:211], 0
	v_mfma_f32_16x16x32_bf16 v[72:75], v[158:161], v[216:219], 0
	v_mfma_f32_16x16x32_bf16 v[64:67], v[166:169], v[216:219], 0
	v_mfma_f32_16x16x32_bf16 v[120:123], v[162:165], v[178:181], v[120:123]
	v_mfma_f32_16x16x32_bf16 v[112:115], v[170:173], v[178:181], v[112:115]
	v_mfma_f32_16x16x32_bf16 v[104:107], v[162:165], v[186:189], v[104:107]
	v_mfma_f32_16x16x32_bf16 v[96:99], v[170:173], v[186:189], v[96:99]
	v_mfma_f32_16x16x32_bf16 v[88:91], v[162:165], v[212:215], v[88:91]
	v_mfma_f32_16x16x32_bf16 v[80:83], v[170:173], v[212:215], v[80:83]
	v_mfma_f32_16x16x32_bf16 v[72:75], v[162:165], v[220:223], v[72:75]
	v_mfma_f32_16x16x32_bf16 v[64:67], v[170:173], v[220:223], v[64:67]
	s_setprio 0
	s_barrier
	s_add_i32 s69, s69, s5
	v_lshl_add_u64 v[190:191], s[36:37], 0, v[194:195]
	s_mov_b32 m0, s69
	ds_read_b128 v[174:177], v145 offset:16384
	ds_read_b128 v[178:181], v145 offset:17408
	ds_read_b128 v[182:185], v145 offset:18432
	ds_read_b128 v[186:189], v145 offset:19456
	ds_read_b128 v[208:211], v145 offset:20480
	ds_read_b128 v[212:215], v145 offset:21504
	ds_read_b128 v[216:219], v145 offset:22528
	ds_read_b128 v[220:223], v145 offset:23552
	global_load_lds_dwordx4 v[190:191], off
	s_add_i32 m0, s69, 0x2000
	s_add_u32 s70, s36, 0x40000
	v_lshl_add_u64 v[226:227], s[36:37], 0, v[128:129]
	s_addc_u32 s71, s37, 0
	s_add_i32 s69, s72, s5
	global_load_lds_dwordx4 v[226:227], off
	v_lshl_add_u64 v[228:229], s[70:71], 0, v[194:195]
	s_mov_b32 m0, s69
	v_lshl_add_u64 v[230:231], s[38:39], 0, v[130:131]
	global_load_lds_dwordx4 v[228:229], off
	v_lshl_add_u64 v[228:229], s[70:71], 0, v[128:129]
	s_add_i32 m0, s69, 0x2000
	s_nop 0
	global_load_lds_dwordx4 v[228:229], off
	v_lshl_add_u64 v[228:229], s[38:39], 0, v[132:133]
	s_mov_b32 m0, s40
	s_nop 0
	global_load_lds_dwordx4 v[228:229], off
	s_mov_b32 m0, s41
	s_nop 0
	global_load_lds_dwordx4 v[230:231], off
	s_waitcnt vmcnt(8)
	s_waitcnt lgkmcnt(0)
	s_barrier
; #define PG8_STAGE(bufoff, gbase, voff) do { _Pragma("unroll") for (int _i = 0; _i < 2; ++_i) \
;         __builtin_amdgcn_global_load_lds((const unsigned*)((const char*)(gbase) + (voff)[_i]), (LAS unsigned*)(lds + (bufoff) + ldsw + _i * 8192), 16, 0, 0); } while (0)
; #define PG8_LDA(dst, b, h) do { _Pragma("unroll") for (int m = 0; m < 4; ++m) _Pragma("unroll") for (int k = 0; k < 2; ++k) dst[m][k] = *(const LAS bf16x8*)(lds + PG8_SA(b, h) + aoff + m * 2048 + k * 1024); } while (0)
; #define PG8_LDB(dst, b, h) do { _Pragma("unroll") for (int n = 0; n < 2; ++n) _Pragma("unroll") for (int k = 0; k < 2; ++k) dst[n][k] = *(const LAS bf16x8*)(lds + PG8_SB(b, h) + boff + n * 2048 + k * 1024); } while (0)
; #define PG8_MMA(ai, bj, At, Bt) do { __builtin_amdgcn_s_setprio(1); _Pragma("unroll") for (int m = 0; m < 4; ++m) _Pragma("unroll") for (int n = 0; n < 2; ++n) _Pragma("unroll") for (int k = 0; k < 2; ++k) \
;         acc[ai][bj][m][n] = __builtin_amdgcn_mfma_f32_16x16x32_bf16(Bt[n][k], At[m][k], acc[ai][bj][m][n], 0, 0, 0); __builtin_amdgcn_s_setprio(0); } while (0)
; #define PG8_WAIT_V(n) asm volatile("s_waitcnt vmcnt(" #n ")" ::: "memory")
; #define PG8_WAIT_L(n) asm volatile("s_waitcnt lgkmcnt(" #n ")" ::: "memory")
; #define PG8_BAR __builtin_amdgcn_s_barrier()
; #define PG8_SCHED __builtin_amdgcn_sched_barrier(0)
; template <class Epi, class Sched, bool ALIGN_EPI = true, bool SP2 = true>
; __device__ __forceinline__ void gemm_phase(LAS unsigned char* lds, const int K, const Sched& S, const Epi& E) {
;     ...
;             PG8_WAIT_V(8); PG8_WAIT_L(0); PG8_BAR; PG8_MMA(1, 0, At, B0); PG8_MMA(1, 1, At, B1); PG8_BAR; PG8_SCHED;
;             PG8_LDB(B0, 1, 0); PG8_LDB(B1, 1, 1); PG8_SCHED; PG8_LDA(At, 1, 0); PG8_STAGE(PG8_SA(0, 1), a2 + hstep, voffA);
;             PG8_WAIT_V(8); PG8_WAIT_L(0); PG8_BAR; PG8_MMA(0, 0, At, B0); PG8_MMA(0, 1, At, B1); PG8_BAR; PG8_SCHED;
	s_setprio 1
	s_waitcnt lgkmcnt(0)
	v_mfma_f32_16x16x32_bf16 v[60:63], v[138:141], v[174:177], 0
	v_mfma_f32_16x16x32_bf16 v[52:55], v[150:153], v[174:177], 0
	v_mfma_f32_16x16x32_bf16 v[44:47], v[138:141], v[182:185], 0
	v_mfma_f32_16x16x32_bf16 v[36:39], v[150:153], v[182:185], 0
	v_mfma_f32_16x16x32_bf16 v[28:31], v[138:141], v[208:211], 0
	v_mfma_f32_16x16x32_bf16 v[20:23], v[150:153], v[208:211], 0
	v_mfma_f32_16x16x32_bf16 v[12:15], v[138:141], v[216:219], 0
	v_mfma_f32_16x16x32_bf16 v[4:7], v[150:153], v[216:219], 0
	v_mfma_f32_16x16x32_bf16 v[60:63], v[146:149], v[178:181], v[60:63]
	v_mfma_f32_16x16x32_bf16 v[52:55], v[154:157], v[178:181], v[52:55]
	v_mfma_f32_16x16x32_bf16 v[44:47], v[146:149], v[186:189], v[44:47]
	v_mfma_f32_16x16x32_bf16 v[36:39], v[154:157], v[186:189], v[36:39]
	v_mfma_f32_16x16x32_bf16 v[28:31], v[146:149], v[212:215], v[28:31]
	v_mfma_f32_16x16x32_bf16 v[20:23], v[154:157], v[212:215], v[20:23]
	v_mfma_f32_16x16x32_bf16 v[12:15], v[146:149], v[220:223], v[12:15]
	v_mfma_f32_16x16x32_bf16 v[4:7], v[154:157], v[220:223], v[4:7]
	s_setprio 0
	s_setprio 1
	v_mfma_f32_16x16x32_bf16 v[56:59], v[158:161], v[174:177], 0
	v_mfma_f32_16x16x32_bf16 v[48:51], v[166:169], v[174:177], 0
	v_mfma_f32_16x16x32_bf16 v[40:43], v[158:161], v[182:185], 0
	v_mfma_f32_16x16x32_bf16 v[32:35], v[166:169], v[182:185], 0
	v_mfma_f32_16x16x32_bf16 v[24:27], v[158:161], v[208:211], 0
	v_mfma_f32_16x16x32_bf16 v[16:19], v[166:169], v[208:211], 0
	v_mfma_f32_16x16x32_bf16 v[8:11], v[158:161], v[216:219], 0
	v_mfma_f32_16x16x32_bf16 v[0:3], v[166:169], v[216:219], 0
	v_mfma_f32_16x16x32_bf16 v[56:59], v[162:165], v[178:181], v[56:59]
	v_mfma_f32_16x16x32_bf16 v[48:51], v[170:173], v[178:181], v[48:51]
	v_mfma_f32_16x16x32_bf16 v[40:43], v[162:165], v[186:189], v[40:43]
	v_mfma_f32_16x16x32_bf16 v[32:35], v[170:173], v[186:189], v[32:35]
	v_mfma_f32_16x16x32_bf16 v[24:27], v[162:165], v[212:215], v[24:27]
	v_mfma_f32_16x16x32_bf16 v[16:19], v[170:173], v[212:215], v[16:19]
	v_mfma_f32_16x16x32_bf16 v[8:11], v[162:165], v[220:223], v[8:11]
	v_mfma_f32_16x16x32_bf16 v[0:3], v[170:173], v[220:223], v[0:3]
	s_setprio 0
	s_barrier
	s_add_i32 s69, 0, 0x18000
	s_add_i32 s70, 0, 0x1c000
	v_add_u32_e32 v154, s69, v144
	v_add_u32_e32 v170, s70, v144
	ds_read_b128 v[138:141], v154
	ds_read_b128 v[146:149], v154 offset:1024
	ds_read_b128 v[150:153], v154 offset:2048
	ds_read_b128 v[154:157], v154 offset:3072
	ds_read_b128 v[158:161], v170
	ds_read_b128 v[162:165], v170 offset:1024
	ds_read_b128 v[166:169], v170 offset:2048
	ds_read_b128 v[170:173], v170 offset:3072
	s_add_u32 s38, s38, 0x40000
	s_addc_u32 s39, s39, 0
	s_mov_b32 m0, s42
	v_lshl_add_u64 v[232:233], s[38:39], 0, v[132:133]
	ds_read_b128 v[174:177], v145 offset:32768
	ds_read_b128 v[178:181], v145 offset:33792
	ds_read_b128 v[182:185], v145 offset:34816
	ds_read_b128 v[186:189], v145 offset:35840
	ds_read_b128 v[208:211], v145 offset:36864
	ds_read_b128 v[212:215], v145 offset:37888
	ds_read_b128 v[216:219], v145 offset:38912
	ds_read_b128 v[220:223], v145 offset:39936
	global_load_lds_dwordx4 v[232:233], off
	v_lshl_add_u64 v[232:233], s[38:39], 0, v[130:131]
	s_mov_b32 m0, s43
	s_nop 0
	global_load_lds_dwordx4 v[232:233], off
	s_waitcnt vmcnt(8)
	s_waitcnt lgkmcnt(0)
	s_barrier
	s_setprio 1
	s_waitcnt lgkmcnt(0)
	v_mfma_f32_16x16x32_bf16 v[124:127], v[138:141], v[174:177], v[124:127]
	v_mfma_f32_16x16x32_bf16 v[116:119], v[150:153], v[174:177], v[116:119]
	v_mfma_f32_16x16x32_bf16 v[108:111], v[138:141], v[182:185], v[108:111]
	v_mfma_f32_16x16x32_bf16 v[100:103], v[150:153], v[182:185], v[100:103]
	v_mfma_f32_16x16x32_bf16 v[92:95], v[138:141], v[208:211], v[92:95]
	v_mfma_f32_16x16x32_bf16 v[84:87], v[150:153], v[208:211], v[84:87]
	v_mfma_f32_16x16x32_bf16 v[76:79], v[138:141], v[216:219], v[76:79]
	v_mfma_f32_16x16x32_bf16 v[68:71], v[150:153], v[216:219], v[68:71]
	v_mfma_f32_16x16x32_bf16 v[124:127], v[146:149], v[178:181], v[124:127]
	v_mfma_f32_16x16x32_bf16 v[116:119], v[154:157], v[178:181], v[116:119]
	v_mfma_f32_16x16x32_bf16 v[108:111], v[146:149], v[186:189], v[108:111]
	v_mfma_f32_16x16x32_bf16 v[100:103], v[154:157], v[186:189], v[100:103]
	v_mfma_f32_16x16x32_bf16 v[92:95], v[146:149], v[212:215], v[92:95]
	v_mfma_f32_16x16x32_bf16 v[84:87], v[154:157], v[212:215], v[84:87]
	v_mfma_f32_16x16x32_bf16 v[76:79], v[146:149], v[220:223], v[76:79]
	v_mfma_f32_16x16x32_bf16 v[68:71], v[154:157], v[220:223], v[68:71]
	s_setprio 0
	s_setprio 1
	v_mfma_f32_16x16x32_bf16 v[120:123], v[158:161], v[174:177], v[120:123]
	v_mfma_f32_16x16x32_bf16 v[112:115], v[166:169], v[174:177], v[112:115]
	v_mfma_f32_16x16x32_bf16 v[104:107], v[158:161], v[182:185], v[104:107]
	v_mfma_f32_16x16x32_bf16 v[96:99], v[166:169], v[182:185], v[96:99]
	v_mfma_f32_16x16x32_bf16 v[88:91], v[158:161], v[208:211], v[88:91]
	v_mfma_f32_16x16x32_bf16 v[80:83], v[166:169], v[208:211], v[80:83]
	v_mfma_f32_16x16x32_bf16 v[72:75], v[158:161], v[216:219], v[72:75]
	v_mfma_f32_16x16x32_bf16 v[64:67], v[166:169], v[216:219], v[64:67]
	v_mfma_f32_16x16x32_bf16 v[120:123], v[162:165], v[178:181], v[120:123]
	v_mfma_f32_16x16x32_bf16 v[112:115], v[170:173], v[178:181], v[112:115]
	v_mfma_f32_16x16x32_bf16 v[104:107], v[162:165], v[186:189], v[104:107]
	v_mfma_f32_16x16x32_bf16 v[96:99], v[170:173], v[186:189], v[96:99]
	v_mfma_f32_16x16x32_bf16 v[88:91], v[162:165], v[212:215], v[88:91]
	v_mfma_f32_16x16x32_bf16 v[80:83], v[170:173], v[212:215], v[80:83]
	v_mfma_f32_16x16x32_bf16 v[72:75], v[162:165], v[220:223], v[72:75]
	v_mfma_f32_16x16x32_bf16 v[64:67], v[170:173], v[220:223], v[64:67]
	s_setprio 0
	s_barrier
; #define PG8_STAGE(bufoff, gbase, voff) do { _Pragma("unroll") for (int _i = 0; _i < 2; ++_i) \
;         __builtin_amdgcn_global_load_lds((const unsigned*)((const char*)(gbase) + (voff)[_i]), (LAS unsigned*)(lds + (bufoff) + ldsw + _i * 8192), 16, 0, 0); } while (0)
; #define PG8_LDA(dst, b, h) do { _Pragma("unroll") for (int m = 0; m < 4; ++m) _Pragma("unroll") for (int k = 0; k < 2; ++k) dst[m][k] = *(const LAS bf16x8*)(lds + PG8_SA(b, h) + aoff + m * 2048 + k * 1024); } while (0)
; #define PG8_MMA(ai, bj, At, Bt) do { __builtin_amdgcn_s_setprio(1); _Pragma("unroll") for (int m = 0; m < 4; ++m) _Pragma("unroll") for (int n = 0; n < 2; ++n) _Pragma("unroll") for (int k = 0; k < 2; ++k) \
;         acc[ai][bj][m][n] = __builtin_amdgcn_mfma_f32_16x16x32_bf16(Bt[n][k], At[m][k], acc[ai][bj][m][n], 0, 0, 0); __builtin_amdgcn_s_setprio(0); } while (0)
; #define PG8_WAIT_V(n) asm volatile("s_waitcnt vmcnt(" #n ")" ::: "memory")
; #define PG8_WAIT_L(n) asm volatile("s_waitcnt lgkmcnt(" #n ")" ::: "memory")
; #define PG8_BAR __builtin_amdgcn_s_barrier()
; #define PG8_SCHED __builtin_amdgcn_sched_barrier(0)
; template <class Epi, class Sched, bool ALIGN_EPI = true, bool SP2 = true>
; __device__ __forceinline__ void gemm_phase(LAS unsigned char* lds, const int K, const Sched& S, const Epi& E) {
;     ...
;             PG8_LDA(At, 1, 1); PG8_STAGE(PG8_SB(1, 0), b3, voffB); PG8_STAGE(PG8_SB(1, 1), b3 + hstep, voffB); PG8_STAGE(PG8_SA(1, 0), a3, voffA);
;             PG8_WAIT_V(8); PG8_WAIT_L(0); PG8_BAR; PG8_MMA(1, 0, At, B0); PG8_MMA(1, 1, At, B1); PG8_BAR; PG8_SCHED;
	s_add_i32 s38, s69, s5
	v_lshl_add_u64 v[190:191], v[190:191], 0, s[94:95]
	s_mov_b32 m0, s38
	ds_read_b128 v[174:177], v145 offset:49152
	ds_read_b128 v[178:181], v145 offset:50176
	ds_read_b128 v[182:185], v145 offset:51200
	ds_read_b128 v[186:189], v145 offset:52224
	ds_read_b128 v[208:211], v145 offset:53248
	ds_read_b128 v[212:215], v145 offset:54272
	ds_read_b128 v[216:219], v145 offset:55296
	ds_read_b128 v[220:223], v145 offset:56320
	global_load_lds_dwordx4 v[190:191], off
	s_add_i32 m0, s38, 0x2000
	s_add_u32 s36, s36, 0x40080
	v_lshl_add_u64 v[190:191], v[226:227], 0, s[94:95]
	s_addc_u32 s37, s37, 0
	s_add_i32 s38, s70, s5
	global_load_lds_dwordx4 v[190:191], off
	v_lshl_add_u64 v[190:191], s[36:37], 0, v[194:195]
	s_mov_b32 m0, s38
	s_nop 0
	global_load_lds_dwordx4 v[190:191], off
	v_lshl_add_u64 v[190:191], s[36:37], 0, v[128:129]
	s_add_i32 m0, s38, 0x2000
	s_nop 0
	global_load_lds_dwordx4 v[190:191], off
	v_lshl_add_u64 v[190:191], v[228:229], 0, s[94:95]
	s_mov_b32 m0, s57
	s_nop 0
	global_load_lds_dwordx4 v[190:191], off
	v_lshl_add_u64 v[190:191], v[230:231], 0, s[94:95]
	s_mov_b32 m0, s58
	s_nop 0
	global_load_lds_dwordx4 v[190:191], off
	s_waitcnt vmcnt(8)
	s_waitcnt lgkmcnt(0)
	s_barrier
	s_setprio 1
	s_waitcnt lgkmcnt(0)
	v_mfma_f32_16x16x32_bf16 v[60:63], v[138:141], v[174:177], v[60:63]
	v_mfma_f32_16x16x32_bf16 v[52:55], v[150:153], v[174:177], v[52:55]
	v_mfma_f32_16x16x32_bf16 v[44:47], v[138:141], v[182:185], v[44:47]
	v_mfma_f32_16x16x32_bf16 v[36:39], v[150:153], v[182:185], v[36:39]
	v_mfma_f32_16x16x32_bf16 v[28:31], v[138:141], v[208:211], v[28:31]
	v_mfma_f32_16x16x32_bf16 v[20:23], v[150:153], v[208:211], v[20:23]
	v_mfma_f32_16x16x32_bf16 v[12:15], v[138:141], v[216:219], v[12:15]
	v_mfma_f32_16x16x32_bf16 v[4:7], v[150:153], v[216:219], v[4:7]
	v_mfma_f32_16x16x32_bf16 v[60:63], v[146:149], v[178:181], v[60:63]
	v_mfma_f32_16x16x32_bf16 v[52:55], v[154:157], v[178:181], v[52:55]
	v_mfma_f32_16x16x32_bf16 v[44:47], v[146:149], v[186:189], v[44:47]
	v_mfma_f32_16x16x32_bf16 v[36:39], v[154:157], v[186:189], v[36:39]
	v_mfma_f32_16x16x32_bf16 v[28:31], v[146:149], v[212:215], v[28:31]
	v_mfma_f32_16x16x32_bf16 v[20:23], v[154:157], v[212:215], v[20:23]
	v_mfma_f32_16x16x32_bf16 v[12:15], v[146:149], v[220:223], v[12:15]
	v_mfma_f32_16x16x32_bf16 v[4:7], v[154:157], v[220:223], v[4:7]
	s_setprio 0
	s_setprio 1
	v_mfma_f32_16x16x32_bf16 v[56:59], v[158:161], v[174:177], v[56:59]
	v_mfma_f32_16x16x32_bf16 v[48:51], v[166:169], v[174:177], v[48:51]
	v_mfma_f32_16x16x32_bf16 v[40:43], v[158:161], v[182:185], v[40:43]
	v_mfma_f32_16x16x32_bf16 v[32:35], v[166:169], v[182:185], v[32:35]
	v_mfma_f32_16x16x32_bf16 v[24:27], v[158:161], v[208:211], v[24:27]
	v_mfma_f32_16x16x32_bf16 v[16:19], v[166:169], v[208:211], v[16:19]
	v_mfma_f32_16x16x32_bf16 v[8:11], v[158:161], v[216:219], v[8:11]
	v_mfma_f32_16x16x32_bf16 v[0:3], v[166:169], v[216:219], v[0:3]
	v_mfma_f32_16x16x32_bf16 v[56:59], v[162:165], v[178:181], v[56:59]
	v_mfma_f32_16x16x32_bf16 v[48:51], v[170:173], v[178:181], v[48:51]
	v_mfma_f32_16x16x32_bf16 v[40:43], v[162:165], v[186:189], v[40:43]
	v_mfma_f32_16x16x32_bf16 v[32:35], v[170:173], v[186:189], v[32:35]
	v_mfma_f32_16x16x32_bf16 v[24:27], v[162:165], v[212:215], v[24:27]
	v_mfma_f32_16x16x32_bf16 v[16:19], v[170:173], v[212:215], v[16:19]
	v_mfma_f32_16x16x32_bf16 v[8:11], v[162:165], v[220:223], v[8:11]
	v_mfma_f32_16x16x32_bf16 v[0:3], v[170:173], v[220:223], v[0:3]
	s_setprio 0
	s_barrier
	s_add_i32 s68, s68, 2
	s_add_u32 s18, s18, 0x100
	s_addc_u32 s19, s19, 0
	s_add_u32 s11, s11, 0x100
	s_addc_u32 s13, s13, 0
	s_cmp_gt_u32 s68, 13

; #define PG8_STAGE(bufoff, gbase, voff) do { _Pragma("unroll") for (int _i = 0; _i < 2; ++_i) \
;         __builtin_amdgcn_global_load_lds((const unsigned*)((const char*)(gbase) + (voff)[_i]), (LAS unsigned*)(lds + (bufoff) + ldsw + _i * 8192), 16, 0, 0); } while (0)
; #define PG8_LDA(dst, b, h) do { _Pragma("unroll") for (int m = 0; m < 4; ++m) _Pragma("unroll") for (int k = 0; k < 2; ++k) dst[m][k] = *(const LAS bf16x8*)(lds + PG8_SA(b, h) + aoff + m * 2048 + k * 1024); } while (0)
; #define PG8_LDB(dst, b, h) do { _Pragma("unroll") for (int n = 0; n < 2; ++n) _Pragma("unroll") for (int k = 0; k < 2; ++k) dst[n][k] = *(const LAS bf16x8*)(lds + PG8_SB(b, h) + boff + n * 2048 + k * 1024); } while (0)
; #define PG8_MMA(ai, bj, At, Bt) do { __builtin_amdgcn_s_setprio(1); _Pragma("unroll") for (int m = 0; m < 4; ++m) _Pragma("unroll") for (int n = 0; n < 2; ++n) _Pragma("unroll") for (int k = 0; k < 2; ++k) \
;         acc[ai][bj][m][n] = __builtin_amdgcn_mfma_f32_16x16x32_bf16(Bt[n][k], At[m][k], acc[ai][bj][m][n], 0, 0, 0); __builtin_amdgcn_s_setprio(0); } while (0)
; template <class Epi, class Sched, bool ALIGN_EPI = true, bool SP2 = true>
; __device__ __forceinline__ void gemm_phase(LAS unsigned char* lds, const int K, const Sched& S, const Epi& E) {
;     ...
;     f32x4 acc[2][2][4][2];
; #pragma unroll
;     for (int a = 0; a < 2; ++a)
; #pragma unroll
;         for (int b = 0; b < 2; ++b)
; #pragma unroll
;             for (int m = 0; m < 4; ++m)
; #pragma unroll
;                 for (int n = 0; n < 2; ++n) acc[a][b][m][n] = (f32x4){0.f, 0.f, 0.f, 0.f};
;     ...
;         for (int t = 0; t < nt; t += 2) {
;             const bool last = (t == nt - 2);
;             const char* a1 = cA + (size_t)(t + 1) * kstep;
;             const char* a2 = last ? nA : cA + (size_t)(t + 2) * kstep; const char* b2 = last ? nB : cB + (size_t)(t + 2) * kstep;
;             const char* a3 = a2 + kstep; const char* b3 = b2 + kstep;
;             if constexpr (SP2) {
;             PG8_LDB(B0, 0, 0); PG8_LDB(B1, 0, 1); PG8_SCHED; PG8_LDA(At, 0, 0); PG8_STAGE(PG8_SA(1, 1), a1 + hstep, voffA);
;             PG8_WAIT_V(8); PG8_WAIT_L(0); PG8_BAR; PG8_MMA(0, 0, At, B0); PG8_MMA(0, 1, At, B1); PG8_BAR; PG8_SCHED;
;             PG8_LDA(At, 0, 1); PG8_STAGE(PG8_SB(0, 0), b2, voffB); PG8_STAGE(PG8_SB(0, 1), b2 + hstep, voffB); PG8_STAGE(PG8_SA(0, 0), a2, voffA);
.LBB0_256:
	s_add_i32 s76, s75, -2
	s_add_u32 s80, s16, 0x100
	s_addc_u32 s81, s17, 0
	s_mov_b32 s18, 0
	s_add_i32 vcc_lo, s18, 2
	s_add_u32 s16, s14, 0x100
	s_addc_u32 s17, s15, 0
	s_add_i32 s78, 0, 0x10000
	s_cmp_eq_u32 s76, s18
	s_cselect_b32 s37, s11, s17
	s_cselect_b32 s36, s10, s16
	s_cselect_b32 s19, s13, s81
	s_cselect_b32 s18, s12, s80
	s_add_i32 s79, 0, 0x14000
	v_add_u32_e32 v150, s78, v164
	v_add_u32_e32 v170, s79, v164
	ds_read_b128 v[138:141], v150
	ds_read_b128 v[142:145], v150 offset:1024
	ds_read_b128 v[146:149], v150 offset:2048
	ds_read_b128 v[150:153], v150 offset:3072
	ds_read_b128 v[154:157], v170
	ds_read_b128 v[158:161], v170 offset:1024
	ds_read_b128 v[166:169], v170 offset:2048
	ds_read_b128 v[170:173], v170 offset:3072
	v_lshl_add_u64 v[190:191], s[14:15], 0, v[134:135]
	s_add_i32 m0, s41, 0xc000
	ds_read_b128 v[174:177], v165
	ds_read_b128 v[178:181], v165 offset:1024
	ds_read_b128 v[182:185], v165 offset:2048
	ds_read_b128 v[186:189], v165 offset:3072
	ds_read_b128 v[208:211], v165 offset:4096
	ds_read_b128 v[212:215], v165 offset:5120
	ds_read_b128 v[216:219], v165 offset:6144
	ds_read_b128 v[220:223], v165 offset:7168
	global_load_lds_dwordx4 v[190:191], off
	v_lshl_add_u64 v[190:191], s[14:15], 0, v[136:137]
	s_add_i32 m0, s41, 0xe000
	s_nop 0
	global_load_lds_dwordx4 v[190:191], off
	s_waitcnt vmcnt(8)
	s_waitcnt lgkmcnt(0)
	s_barrier
	s_setprio 1
	s_waitcnt lgkmcnt(0)
	v_mfma_f32_16x16x32_bf16 v[124:127], v[138:141], v[174:177], 0
	v_mfma_f32_16x16x32_bf16 v[120:123], v[146:149], v[174:177], 0
	v_mfma_f32_16x16x32_bf16 v[116:119], v[138:141], v[182:185], 0
	v_mfma_f32_16x16x32_bf16 v[112:115], v[146:149], v[182:185], 0
	v_mfma_f32_16x16x32_bf16 v[104:107], v[138:141], v[208:211], 0
	v_mfma_f32_16x16x32_bf16 v[96:99], v[146:149], v[208:211], 0
	v_mfma_f32_16x16x32_bf16 v[88:91], v[138:141], v[216:219], 0
	v_mfma_f32_16x16x32_bf16 v[80:83], v[146:149], v[216:219], 0
	v_mfma_f32_16x16x32_bf16 v[124:127], v[142:145], v[178:181], v[124:127]
	v_mfma_f32_16x16x32_bf16 v[120:123], v[150:153], v[178:181], v[120:123]
	v_mfma_f32_16x16x32_bf16 v[116:119], v[142:145], v[186:189], v[116:119]
	v_mfma_f32_16x16x32_bf16 v[112:115], v[150:153], v[186:189], v[112:115]
	v_mfma_f32_16x16x32_bf16 v[104:107], v[142:145], v[212:215], v[104:107]
	v_mfma_f32_16x16x32_bf16 v[96:99], v[150:153], v[212:215], v[96:99]
	v_mfma_f32_16x16x32_bf16 v[88:91], v[142:145], v[220:223], v[88:91]
	v_mfma_f32_16x16x32_bf16 v[80:83], v[150:153], v[220:223], v[80:83]
	s_setprio 0
	s_setprio 1
	v_mfma_f32_16x16x32_bf16 v[108:111], v[154:157], v[174:177], 0
	v_mfma_f32_16x16x32_bf16 v[100:103], v[166:169], v[174:177], 0
	v_mfma_f32_16x16x32_bf16 v[92:95], v[154:157], v[182:185], 0
	v_mfma_f32_16x16x32_bf16 v[84:87], v[166:169], v[182:185], 0
	v_mfma_f32_16x16x32_bf16 v[76:79], v[154:157], v[208:211], 0
	v_mfma_f32_16x16x32_bf16 v[72:75], v[166:169], v[208:211], 0
	v_mfma_f32_16x16x32_bf16 v[68:71], v[154:157], v[216:219], 0
	v_mfma_f32_16x16x32_bf16 v[64:67], v[166:169], v[216:219], 0
	v_mfma_f32_16x16x32_bf16 v[108:111], v[158:161], v[178:181], v[108:111]
	v_mfma_f32_16x16x32_bf16 v[100:103], v[170:173], v[178:181], v[100:103]
	v_mfma_f32_16x16x32_bf16 v[92:95], v[158:161], v[186:189], v[92:95]
	v_mfma_f32_16x16x32_bf16 v[84:87], v[170:173], v[186:189], v[84:87]
	v_mfma_f32_16x16x32_bf16 v[76:79], v[158:161], v[212:215], v[76:79]
	v_mfma_f32_16x16x32_bf16 v[72:75], v[170:173], v[212:215], v[72:75]
	v_mfma_f32_16x16x32_bf16 v[68:71], v[158:161], v[220:223], v[68:71]
	v_mfma_f32_16x16x32_bf16 v[64:67], v[170:173], v[220:223], v[64:67]
	s_setprio 0
	s_barrier
	s_add_i32 s14, s78, s40
	v_lshl_add_u64 v[190:191], s[18:19], 0, v[194:195]
	s_mov_b32 m0, s14
	ds_read_b128 v[174:177], v165 offset:16384
	ds_read_b128 v[178:181], v165 offset:17408
	ds_read_b128 v[182:185], v165 offset:18432
	ds_read_b128 v[186:189], v165 offset:19456
	ds_read_b128 v[208:211], v165 offset:20480
	ds_read_b128 v[212:215], v165 offset:21504
	ds_read_b128 v[216:219], v165 offset:22528
	ds_read_b128 v[220:223], v165 offset:23552
	global_load_lds_dwordx4 v[190:191], off
	s_add_i32 m0, s14, 0x2000
	s_add_u32 s14, s18, 0xb0000
	v_lshl_add_u64 v[226:227], s[18:19], 0, v[132:133]
	s_addc_u32 s15, s19, 0
	s_add_i32 s78, s79, s40
	global_load_lds_dwordx4 v[226:227], off
	v_lshl_add_u64 v[228:229], s[14:15], 0, v[194:195]
	s_mov_b32 m0, s78
	v_lshl_add_u64 v[230:231], s[36:37], 0, v[130:131]
	global_load_lds_dwordx4 v[228:229], off
	v_lshl_add_u64 v[228:229], s[14:15], 0, v[132:133]
	s_add_i32 m0, s78, 0x2000
	s_nop 0
	global_load_lds_dwordx4 v[228:229], off
	v_lshl_add_u64 v[228:229], s[36:37], 0, v[128:129]
	s_mov_b32 m0, s41
	s_nop 0
	global_load_lds_dwordx4 v[228:229], off
	s_mov_b32 m0, s42
	s_nop 0
	global_load_lds_dwordx4 v[230:231], off
	s_waitcnt vmcnt(8)
	s_waitcnt lgkmcnt(0)
	s_barrier
; #define PG8_STAGE(bufoff, gbase, voff) do { _Pragma("unroll") for (int _i = 0; _i < 2; ++_i) \
;         __builtin_amdgcn_global_load_lds((const unsigned*)((const char*)(gbase) + (voff)[_i]), (LAS unsigned*)(lds + (bufoff) + ldsw + _i * 8192), 16, 0, 0); } while (0)
; #define PG8_LDA(dst, b, h) do { _Pragma("unroll") for (int m = 0; m < 4; ++m) _Pragma("unroll") for (int k = 0; k < 2; ++k) dst[m][k] = *(const LAS bf16x8*)(lds + PG8_SA(b, h) + aoff + m * 2048 + k * 1024); } while (0)
; #define PG8_LDB(dst, b, h) do { _Pragma("unroll") for (int n = 0; n < 2; ++n) _Pragma("unroll") for (int k = 0; k < 2; ++k) dst[n][k] = *(const LAS bf16x8*)(lds + PG8_SB(b, h) + boff + n * 2048 + k * 1024); } while (0)
; #define PG8_MMA(ai, bj, At, Bt) do { __builtin_amdgcn_s_setprio(1); _Pragma("unroll") for (int m = 0; m < 4; ++m) _Pragma("unroll") for (int n = 0; n < 2; ++n) _Pragma("unroll") for (int k = 0; k < 2; ++k) \
;         acc[ai][bj][m][n] = __builtin_amdgcn_mfma_f32_16x16x32_bf16(Bt[n][k], At[m][k], acc[ai][bj][m][n], 0, 0, 0); __builtin_amdgcn_s_setprio(0); } while (0)
; #define PG8_WAIT_V(n) asm volatile("s_waitcnt vmcnt(" #n ")" ::: "memory")
; #define PG8_WAIT_L(n) asm volatile("s_waitcnt lgkmcnt(" #n ")" ::: "memory")
; #define PG8_BAR __builtin_amdgcn_s_barrier()
; #define PG8_SCHED __builtin_amdgcn_sched_barrier(0)
; template <class Epi, class Sched, bool ALIGN_EPI = true, bool SP2 = true>
; __device__ __forceinline__ void gemm_phase(LAS unsigned char* lds, const int K, const Sched& S, const Epi& E) {
;     ...
;             PG8_WAIT_V(8); PG8_WAIT_L(0); PG8_BAR; PG8_MMA(1, 0, At, B0); PG8_MMA(1, 1, At, B1); PG8_BAR; PG8_SCHED;
;             PG8_LDB(B0, 1, 0); PG8_LDB(B1, 1, 1); PG8_SCHED; PG8_LDA(At, 1, 0); PG8_STAGE(PG8_SA(0, 1), a2 + hstep, voffA);
;             PG8_WAIT_V(8); PG8_WAIT_L(0); PG8_BAR; PG8_MMA(0, 0, At, B0); PG8_MMA(0, 1, At, B1); PG8_BAR; PG8_SCHED;
	s_setprio 1
	s_waitcnt lgkmcnt(0)
	v_mfma_f32_16x16x32_bf16 v[60:63], v[138:141], v[174:177], 0
	v_mfma_f32_16x16x32_bf16 v[56:59], v[146:149], v[174:177], 0
	v_mfma_f32_16x16x32_bf16 v[52:55], v[138:141], v[182:185], 0
	v_mfma_f32_16x16x32_bf16 v[48:51], v[146:149], v[182:185], 0
	v_mfma_f32_16x16x32_bf16 v[40:43], v[138:141], v[208:211], 0
	v_mfma_f32_16x16x32_bf16 v[32:35], v[146:149], v[208:211], 0
	v_mfma_f32_16x16x32_bf16 v[24:27], v[138:141], v[216:219], 0
	v_mfma_f32_16x16x32_bf16 v[16:19], v[146:149], v[216:219], 0
	v_mfma_f32_16x16x32_bf16 v[60:63], v[142:145], v[178:181], v[60:63]
	v_mfma_f32_16x16x32_bf16 v[56:59], v[150:153], v[178:181], v[56:59]
	v_mfma_f32_16x16x32_bf16 v[52:55], v[142:145], v[186:189], v[52:55]
	v_mfma_f32_16x16x32_bf16 v[48:51], v[150:153], v[186:189], v[48:51]
	v_mfma_f32_16x16x32_bf16 v[40:43], v[142:145], v[212:215], v[40:43]
	v_mfma_f32_16x16x32_bf16 v[32:35], v[150:153], v[212:215], v[32:35]
	v_mfma_f32_16x16x32_bf16 v[24:27], v[142:145], v[220:223], v[24:27]
	v_mfma_f32_16x16x32_bf16 v[16:19], v[150:153], v[220:223], v[16:19]
	s_setprio 0
	s_setprio 1
	v_mfma_f32_16x16x32_bf16 v[44:47], v[154:157], v[174:177], 0
	v_mfma_f32_16x16x32_bf16 v[36:39], v[166:169], v[174:177], 0
	v_mfma_f32_16x16x32_bf16 v[28:31], v[154:157], v[182:185], 0
	v_mfma_f32_16x16x32_bf16 v[20:23], v[166:169], v[182:185], 0
	v_mfma_f32_16x16x32_bf16 v[12:15], v[154:157], v[208:211], 0
	v_mfma_f32_16x16x32_bf16 v[8:11], v[166:169], v[208:211], 0
	v_mfma_f32_16x16x32_bf16 v[4:7], v[154:157], v[216:219], 0
	v_mfma_f32_16x16x32_bf16 v[0:3], v[166:169], v[216:219], 0
	v_mfma_f32_16x16x32_bf16 v[44:47], v[158:161], v[178:181], v[44:47]
	v_mfma_f32_16x16x32_bf16 v[36:39], v[170:173], v[178:181], v[36:39]
	v_mfma_f32_16x16x32_bf16 v[28:31], v[158:161], v[186:189], v[28:31]
	v_mfma_f32_16x16x32_bf16 v[20:23], v[170:173], v[186:189], v[20:23]
	v_mfma_f32_16x16x32_bf16 v[12:15], v[158:161], v[212:215], v[12:15]
	v_mfma_f32_16x16x32_bf16 v[8:11], v[170:173], v[212:215], v[8:11]
	v_mfma_f32_16x16x32_bf16 v[4:7], v[158:161], v[220:223], v[4:7]
	v_mfma_f32_16x16x32_bf16 v[0:3], v[170:173], v[220:223], v[0:3]
	s_setprio 0
	s_barrier
	s_add_i32 s78, 0, 0x18000
	s_add_i32 s79, 0, 0x1c000
	v_add_u32_e32 v150, s78, v164
	v_add_u32_e32 v170, s79, v164
	ds_read_b128 v[138:141], v150
	ds_read_b128 v[142:145], v150 offset:1024
	ds_read_b128 v[146:149], v150 offset:2048
	ds_read_b128 v[150:153], v150 offset:3072
	ds_read_b128 v[154:157], v170
	ds_read_b128 v[158:161], v170 offset:1024
	ds_read_b128 v[166:169], v170 offset:2048
	ds_read_b128 v[170:173], v170 offset:3072
	s_add_u32 s14, s36, 0xb0000
	s_addc_u32 s15, s37, 0
	s_mov_b32 m0, s43
	v_lshl_add_u64 v[232:233], s[14:15], 0, v[128:129]
	ds_read_b128 v[174:177], v165 offset:32768
	ds_read_b128 v[178:181], v165 offset:33792
	ds_read_b128 v[182:185], v165 offset:34816
	ds_read_b128 v[186:189], v165 offset:35840
	ds_read_b128 v[208:211], v165 offset:36864
	ds_read_b128 v[212:215], v165 offset:37888
	ds_read_b128 v[216:219], v165 offset:38912
	ds_read_b128 v[220:223], v165 offset:39936
	global_load_lds_dwordx4 v[232:233], off
	v_lshl_add_u64 v[232:233], s[14:15], 0, v[130:131]
	s_mov_b32 m0, s47
	s_nop 0
	global_load_lds_dwordx4 v[232:233], off
	s_waitcnt vmcnt(8)
	s_waitcnt lgkmcnt(0)
	s_barrier
	s_setprio 1
	s_waitcnt lgkmcnt(0)
	v_mfma_f32_16x16x32_bf16 v[124:127], v[138:141], v[174:177], v[124:127]
	v_mfma_f32_16x16x32_bf16 v[120:123], v[146:149], v[174:177], v[120:123]
	v_mfma_f32_16x16x32_bf16 v[116:119], v[138:141], v[182:185], v[116:119]
	v_mfma_f32_16x16x32_bf16 v[112:115], v[146:149], v[182:185], v[112:115]
	v_mfma_f32_16x16x32_bf16 v[104:107], v[138:141], v[208:211], v[104:107]
	v_mfma_f32_16x16x32_bf16 v[96:99], v[146:149], v[208:211], v[96:99]
	v_mfma_f32_16x16x32_bf16 v[88:91], v[138:141], v[216:219], v[88:91]
	v_mfma_f32_16x16x32_bf16 v[80:83], v[146:149], v[216:219], v[80:83]
	v_mfma_f32_16x16x32_bf16 v[124:127], v[142:145], v[178:181], v[124:127]
	v_mfma_f32_16x16x32_bf16 v[120:123], v[150:153], v[178:181], v[120:123]
	v_mfma_f32_16x16x32_bf16 v[116:119], v[142:145], v[186:189], v[116:119]
	v_mfma_f32_16x16x32_bf16 v[112:115], v[150:153], v[186:189], v[112:115]
	v_mfma_f32_16x16x32_bf16 v[104:107], v[142:145], v[212:215], v[104:107]
	v_mfma_f32_16x16x32_bf16 v[96:99], v[150:153], v[212:215], v[96:99]
	v_mfma_f32_16x16x32_bf16 v[88:91], v[142:145], v[220:223], v[88:91]
	v_mfma_f32_16x16x32_bf16 v[80:83], v[150:153], v[220:223], v[80:83]
	s_setprio 0
	s_setprio 1
	v_mfma_f32_16x16x32_bf16 v[108:111], v[154:157], v[174:177], v[108:111]
	v_mfma_f32_16x16x32_bf16 v[100:103], v[166:169], v[174:177], v[100:103]
	v_mfma_f32_16x16x32_bf16 v[92:95], v[154:157], v[182:185], v[92:95]
	v_mfma_f32_16x16x32_bf16 v[84:87], v[166:169], v[182:185], v[84:87]
	v_mfma_f32_16x16x32_bf16 v[76:79], v[154:157], v[208:211], v[76:79]
	v_mfma_f32_16x16x32_bf16 v[72:75], v[166:169], v[208:211], v[72:75]
	v_mfma_f32_16x16x32_bf16 v[68:71], v[154:157], v[216:219], v[68:71]
	v_mfma_f32_16x16x32_bf16 v[64:67], v[166:169], v[216:219], v[64:67]
	v_mfma_f32_16x16x32_bf16 v[108:111], v[158:161], v[178:181], v[108:111]
	v_mfma_f32_16x16x32_bf16 v[100:103], v[170:173], v[178:181], v[100:103]
	v_mfma_f32_16x16x32_bf16 v[92:95], v[158:161], v[186:189], v[92:95]
	v_mfma_f32_16x16x32_bf16 v[84:87], v[170:173], v[186:189], v[84:87]
	v_mfma_f32_16x16x32_bf16 v[76:79], v[158:161], v[212:215], v[76:79]
	v_mfma_f32_16x16x32_bf16 v[72:75], v[170:173], v[212:215], v[72:75]
	v_mfma_f32_16x16x32_bf16 v[68:71], v[158:161], v[220:223], v[68:71]
	v_mfma_f32_16x16x32_bf16 v[64:67], v[170:173], v[220:223], v[64:67]
	s_setprio 0
	s_barrier
; #define PG8_STAGE(bufoff, gbase, voff) do { _Pragma("unroll") for (int _i = 0; _i < 2; ++_i) \
;         __builtin_amdgcn_global_load_lds((const unsigned*)((const char*)(gbase) + (voff)[_i]), (LAS unsigned*)(lds + (bufoff) + ldsw + _i * 8192), 16, 0, 0); } while (0)
; #define PG8_LDA(dst, b, h) do { _Pragma("unroll") for (int m = 0; m < 4; ++m) _Pragma("unroll") for (int k = 0; k < 2; ++k) dst[m][k] = *(const LAS bf16x8*)(lds + PG8_SA(b, h) + aoff + m * 2048 + k * 1024); } while (0)
; #define PG8_MMA(ai, bj, At, Bt) do { __builtin_amdgcn_s_setprio(1); _Pragma("unroll") for (int m = 0; m < 4; ++m) _Pragma("unroll") for (int n = 0; n < 2; ++n) _Pragma("unroll") for (int k = 0; k < 2; ++k) \
;         acc[ai][bj][m][n] = __builtin_amdgcn_mfma_f32_16x16x32_bf16(Bt[n][k], At[m][k], acc[ai][bj][m][n], 0, 0, 0); __builtin_amdgcn_s_setprio(0); } while (0)
; #define PG8_WAIT_V(n) asm volatile("s_waitcnt vmcnt(" #n ")" ::: "memory")
; #define PG8_WAIT_L(n) asm volatile("s_waitcnt lgkmcnt(" #n ")" ::: "memory")
; #define PG8_BAR __builtin_amdgcn_s_barrier()
; #define PG8_SCHED __builtin_amdgcn_sched_barrier(0)
; template <class Epi, class Sched, bool ALIGN_EPI = true, bool SP2 = true>
; __device__ __forceinline__ void gemm_phase(LAS unsigned char* lds, const int K, const Sched& S, const Epi& E) {
;     ...
;             PG8_LDA(At, 1, 1); PG8_STAGE(PG8_SB(1, 0), b3, voffB); PG8_STAGE(PG8_SB(1, 1), b3 + hstep, voffB); PG8_STAGE(PG8_SA(1, 0), a3, voffA);
;             PG8_WAIT_V(8); PG8_WAIT_L(0); PG8_BAR; PG8_MMA(1, 0, At, B0); PG8_MMA(1, 1, At, B1); PG8_BAR; PG8_SCHED;
	s_add_i32 s14, s78, s40
	v_lshl_add_u64 v[190:191], v[190:191], 0, s[94:95]
	s_mov_b32 m0, s14
	ds_read_b128 v[174:177], v165 offset:49152
	ds_read_b128 v[178:181], v165 offset:50176
	ds_read_b128 v[182:185], v165 offset:51200
	ds_read_b128 v[186:189], v165 offset:52224
	ds_read_b128 v[208:211], v165 offset:53248
	ds_read_b128 v[212:215], v165 offset:54272
	ds_read_b128 v[216:219], v165 offset:55296
	ds_read_b128 v[220:223], v165 offset:56320
	global_load_lds_dwordx4 v[190:191], off
	s_add_i32 m0, s14, 0x2000
	s_add_u32 s14, s18, 0xb0080
	v_lshl_add_u64 v[190:191], v[226:227], 0, s[94:95]
	s_addc_u32 s15, s19, 0
	s_add_i32 s18, s79, s40
	global_load_lds_dwordx4 v[190:191], off
	v_lshl_add_u64 v[190:191], s[14:15], 0, v[194:195]
	s_mov_b32 m0, s18
	s_nop 0
	global_load_lds_dwordx4 v[190:191], off
	v_lshl_add_u64 v[190:191], s[14:15], 0, v[132:133]
	s_add_i32 m0, s18, 0x2000
	s_nop 0
	global_load_lds_dwordx4 v[190:191], off
	v_lshl_add_u64 v[190:191], v[228:229], 0, s[94:95]
	s_mov_b32 m0, s66
	s_nop 0
	global_load_lds_dwordx4 v[190:191], off
	v_lshl_add_u64 v[190:191], v[230:231], 0, s[94:95]
	s_mov_b32 m0, s67
	s_nop 0
	global_load_lds_dwordx4 v[190:191], off
	s_waitcnt vmcnt(8)
	s_waitcnt lgkmcnt(0)
	s_barrier
	s_setprio 1
	s_waitcnt lgkmcnt(0)
	v_mfma_f32_16x16x32_bf16 v[60:63], v[138:141], v[174:177], v[60:63]
	v_mfma_f32_16x16x32_bf16 v[56:59], v[146:149], v[174:177], v[56:59]
	v_mfma_f32_16x16x32_bf16 v[52:55], v[138:141], v[182:185], v[52:55]
	v_mfma_f32_16x16x32_bf16 v[48:51], v[146:149], v[182:185], v[48:51]
	v_mfma_f32_16x16x32_bf16 v[40:43], v[138:141], v[208:211], v[40:43]
	v_mfma_f32_16x16x32_bf16 v[32:35], v[146:149], v[208:211], v[32:35]
	v_mfma_f32_16x16x32_bf16 v[24:27], v[138:141], v[216:219], v[24:27]
	v_mfma_f32_16x16x32_bf16 v[16:19], v[146:149], v[216:219], v[16:19]
	v_mfma_f32_16x16x32_bf16 v[60:63], v[142:145], v[178:181], v[60:63]
	v_mfma_f32_16x16x32_bf16 v[56:59], v[150:153], v[178:181], v[56:59]
	v_mfma_f32_16x16x32_bf16 v[52:55], v[142:145], v[186:189], v[52:55]
	v_mfma_f32_16x16x32_bf16 v[48:51], v[150:153], v[186:189], v[48:51]
	v_mfma_f32_16x16x32_bf16 v[40:43], v[142:145], v[212:215], v[40:43]
	v_mfma_f32_16x16x32_bf16 v[32:35], v[150:153], v[212:215], v[32:35]
	v_mfma_f32_16x16x32_bf16 v[24:27], v[142:145], v[220:223], v[24:27]
	v_mfma_f32_16x16x32_bf16 v[16:19], v[150:153], v[220:223], v[16:19]
	s_setprio 0
	s_setprio 1
	v_mfma_f32_16x16x32_bf16 v[44:47], v[154:157], v[174:177], v[44:47]
	v_mfma_f32_16x16x32_bf16 v[36:39], v[166:169], v[174:177], v[36:39]
	v_mfma_f32_16x16x32_bf16 v[28:31], v[154:157], v[182:185], v[28:31]
	v_mfma_f32_16x16x32_bf16 v[20:23], v[166:169], v[182:185], v[20:23]
	v_mfma_f32_16x16x32_bf16 v[12:15], v[154:157], v[208:211], v[12:15]
	v_mfma_f32_16x16x32_bf16 v[8:11], v[166:169], v[208:211], v[8:11]
	v_mfma_f32_16x16x32_bf16 v[4:7], v[154:157], v[216:219], v[4:7]
	v_mfma_f32_16x16x32_bf16 v[0:3], v[166:169], v[216:219], v[0:3]
	v_mfma_f32_16x16x32_bf16 v[44:47], v[158:161], v[178:181], v[44:47]
	v_mfma_f32_16x16x32_bf16 v[36:39], v[170:173], v[178:181], v[36:39]
	v_mfma_f32_16x16x32_bf16 v[28:31], v[158:161], v[186:189], v[28:31]
	v_mfma_f32_16x16x32_bf16 v[20:23], v[170:173], v[186:189], v[20:23]
	v_mfma_f32_16x16x32_bf16 v[12:15], v[158:161], v[212:215], v[12:15]
	v_mfma_f32_16x16x32_bf16 v[8:11], v[170:173], v[212:215], v[8:11]
	v_mfma_f32_16x16x32_bf16 v[4:7], v[158:161], v[220:223], v[4:7]
	v_mfma_f32_16x16x32_bf16 v[0:3], v[170:173], v[220:223], v[0:3]
	s_setprio 0
	s_barrier
	s_add_u32 s80, s80, 0x100
	s_addc_u32 s81, s81, 0
	s_cmp_ge_i32 vcc_lo, s75
	s_mov_b64 s[14:15], s[16:17]
	s_mov_b32 s18, vcc_lo

; #define PG8_STAGE(bufoff, gbase, voff) do { _Pragma("unroll") for (int _i = 0; _i < 2; ++_i) \
;         __builtin_amdgcn_global_load_lds((const unsigned*)((const char*)(gbase) + (voff)[_i]), (LAS unsigned*)(lds + (bufoff) + ldsw + _i * 8192), 16, 0, 0); } while (0)
; #define PG8_LDA(dst, b, h) do { _Pragma("unroll") for (int m = 0; m < 4; ++m) _Pragma("unroll") for (int k = 0; k < 2; ++k) dst[m][k] = *(const LAS bf16x8*)(lds + PG8_SA(b, h) + aoff + m * 2048 + k * 1024); } while (0)
; #define PG8_LDB(dst, b, h) do { _Pragma("unroll") for (int n = 0; n < 2; ++n) _Pragma("unroll") for (int k = 0; k < 2; ++k) dst[n][k] = *(const LAS bf16x8*)(lds + PG8_SB(b, h) + boff + n * 2048 + k * 1024); } while (0)
; #define PG8_MMA(ai, bj, At, Bt) do { __builtin_amdgcn_s_setprio(1); _Pragma("unroll") for (int m = 0; m < 4; ++m) _Pragma("unroll") for (int n = 0; n < 2; ++n) _Pragma("unroll") for (int k = 0; k < 2; ++k) \
;         acc[ai][bj][m][n] = __builtin_amdgcn_mfma_f32_16x16x32_bf16(Bt[n][k], At[m][k], acc[ai][bj][m][n], 0, 0, 0); __builtin_amdgcn_s_setprio(0); } while (0)
; template <class Epi, class Sched, bool ALIGN_EPI = true, bool SP2 = true>
; __device__ __forceinline__ void gemm_phase(LAS unsigned char* lds, const int K, const Sched& S, const Epi& E) {
;     ...
;     f32x4 acc[2][2][4][2];
; #pragma unroll
;     for (int a = 0; a < 2; ++a)
; #pragma unroll
;         for (int b = 0; b < 2; ++b)
; #pragma unroll
;             for (int m = 0; m < 4; ++m)
; #pragma unroll
;                 for (int n = 0; n < 2; ++n) acc[a][b][m][n] = (f32x4){0.f, 0.f, 0.f, 0.f};
;     ...
;         for (int t = 0; t < nt; t += 2) {
;             const bool last = (t == nt - 2);
;             const char* a1 = cA + (size_t)(t + 1) * kstep;
;             const char* a2 = last ? nA : cA + (size_t)(t + 2) * kstep; const char* b2 = last ? nB : cB + (size_t)(t + 2) * kstep;
;             const char* a3 = a2 + kstep; const char* b3 = b2 + kstep;
;             if constexpr (SP2) {
;             PG8_LDB(B0, 0, 0); PG8_LDB(B1, 0, 1); PG8_SCHED; PG8_LDA(At, 0, 0); PG8_STAGE(PG8_SA(1, 1), a1 + hstep, voffA);
;             PG8_WAIT_V(8); PG8_WAIT_L(0); PG8_BAR; PG8_MMA(0, 0, At, B0); PG8_MMA(0, 1, At, B1); PG8_BAR; PG8_SCHED;
;             PG8_LDA(At, 0, 1); PG8_STAGE(PG8_SB(0, 0), b2, voffB); PG8_STAGE(PG8_SB(0, 1), b2 + hstep, voffB); PG8_STAGE(PG8_SA(0, 0), a2, voffA);
.LBB0_407:
	s_add_u32 s0, s0, 0x40080
	s_addc_u32 s1, s1, 0
	s_add_u32 s11, s18, 0x100
	s_addc_u32 s15, s19, 0
	s_mov_b32 s38, -2
	s_add_u32 s18, s0, 0xfffc0080
	s_addc_u32 s19, s1, -1
	s_add_i32 s39, 0, 0x10000
	s_cmp_eq_u32 s38, 12
	s_cselect_b32 s37, s13, s19
	s_cselect_b32 s36, s12, s18
	s_cselect_b32 s19, s17, s15
	s_cselect_b32 s18, s16, s11
	s_add_i32 s66, 0, 0x14000
	v_add_u32_e32 v152, s39, v233
	v_add_u32_e32 v168, s66, v233
	ds_read_b128 v[140:143], v152
	ds_read_b128 v[144:147], v152 offset:1024
	ds_read_b128 v[148:151], v152 offset:2048
	ds_read_b128 v[152:155], v152 offset:3072
	ds_read_b128 v[156:159], v168
	ds_read_b128 v[160:163], v168 offset:1024
	ds_read_b128 v[164:167], v168 offset:2048
	ds_read_b128 v[168:171], v168 offset:3072
	v_lshl_add_u64 v[220:221], s[0:1], 0, v[136:137]
	s_add_i32 m0, s57, 0xc000
	ds_read_b128 v[172:175], v234
	ds_read_b128 v[176:179], v234 offset:1024
	ds_read_b128 v[180:183], v234 offset:2048
	ds_read_b128 v[184:187], v234 offset:3072
	ds_read_b128 v[188:191], v234 offset:4096
	ds_read_b128 v[208:211], v234 offset:5120
	ds_read_b128 v[212:215], v234 offset:6144
	ds_read_b128 v[216:219], v234 offset:7168
	global_load_lds_dwordx4 v[220:221], off
	v_lshl_add_u64 v[220:221], s[0:1], 0, v[138:139]
	s_add_i32 m0, s57, 0xe000
	s_nop 0
	global_load_lds_dwordx4 v[220:221], off
	s_waitcnt vmcnt(8)
	s_waitcnt lgkmcnt(0)
	s_barrier
	s_setprio 1
	s_waitcnt lgkmcnt(0)
	v_mfma_f32_16x16x32_bf16 v[124:127], v[140:143], v[172:175], 0
	v_mfma_f32_16x16x32_bf16 v[120:123], v[148:151], v[172:175], 0
	v_mfma_f32_16x16x32_bf16 v[116:119], v[140:143], v[180:183], 0
	v_mfma_f32_16x16x32_bf16 v[112:115], v[148:151], v[180:183], 0
	v_mfma_f32_16x16x32_bf16 v[100:103], v[140:143], v[188:191], 0
	v_mfma_f32_16x16x32_bf16 v[96:99], v[148:151], v[188:191], 0
	v_mfma_f32_16x16x32_bf16 v[84:87], v[140:143], v[212:215], 0
	v_mfma_f32_16x16x32_bf16 v[80:83], v[148:151], v[212:215], 0
	v_mfma_f32_16x16x32_bf16 v[124:127], v[144:147], v[176:179], v[124:127]
	v_mfma_f32_16x16x32_bf16 v[120:123], v[152:155], v[176:179], v[120:123]
	v_mfma_f32_16x16x32_bf16 v[116:119], v[144:147], v[184:187], v[116:119]
	v_mfma_f32_16x16x32_bf16 v[112:115], v[152:155], v[184:187], v[112:115]
	v_mfma_f32_16x16x32_bf16 v[100:103], v[144:147], v[208:211], v[100:103]
	v_mfma_f32_16x16x32_bf16 v[96:99], v[152:155], v[208:211], v[96:99]
	v_mfma_f32_16x16x32_bf16 v[84:87], v[144:147], v[216:219], v[84:87]
	v_mfma_f32_16x16x32_bf16 v[80:83], v[152:155], v[216:219], v[80:83]
	s_setprio 0
	s_setprio 1
	v_mfma_f32_16x16x32_bf16 v[108:111], v[156:159], v[172:175], 0
	v_mfma_f32_16x16x32_bf16 v[104:107], v[164:167], v[172:175], 0
	v_mfma_f32_16x16x32_bf16 v[92:95], v[156:159], v[180:183], 0
	v_mfma_f32_16x16x32_bf16 v[88:91], v[164:167], v[180:183], 0
	v_mfma_f32_16x16x32_bf16 v[76:79], v[156:159], v[188:191], 0
	v_mfma_f32_16x16x32_bf16 v[72:75], v[164:167], v[188:191], 0
	v_mfma_f32_16x16x32_bf16 v[68:71], v[156:159], v[212:215], 0
	v_mfma_f32_16x16x32_bf16 v[64:67], v[164:167], v[212:215], 0
	v_mfma_f32_16x16x32_bf16 v[108:111], v[160:163], v[176:179], v[108:111]
	v_mfma_f32_16x16x32_bf16 v[104:107], v[168:171], v[176:179], v[104:107]
	v_mfma_f32_16x16x32_bf16 v[92:95], v[160:163], v[184:187], v[92:95]
	v_mfma_f32_16x16x32_bf16 v[88:91], v[168:171], v[184:187], v[88:91]
	v_mfma_f32_16x16x32_bf16 v[76:79], v[160:163], v[208:211], v[76:79]
	v_mfma_f32_16x16x32_bf16 v[72:75], v[168:171], v[208:211], v[72:75]
	v_mfma_f32_16x16x32_bf16 v[68:71], v[160:163], v[216:219], v[68:71]
	v_mfma_f32_16x16x32_bf16 v[64:67], v[168:171], v[216:219], v[64:67]
	s_setprio 0
	s_barrier
	s_add_i32 s39, s39, s56
	v_lshl_add_u64 v[220:221], s[18:19], 0, v[130:131]
	s_mov_b32 m0, s39
	ds_read_b128 v[172:175], v234 offset:16384
	ds_read_b128 v[176:179], v234 offset:17408
	ds_read_b128 v[180:183], v234 offset:18432
	ds_read_b128 v[184:187], v234 offset:19456
	ds_read_b128 v[188:191], v234 offset:20480
	ds_read_b128 v[208:211], v234 offset:21504
	ds_read_b128 v[212:215], v234 offset:22528
	ds_read_b128 v[216:219], v234 offset:23552
	global_load_lds_dwordx4 v[220:221], off
	s_add_i32 m0, s39, 0x2000
	s_add_u32 s58, s18, 0x40000
	v_lshl_add_u64 v[222:223], s[18:19], 0, v[134:135]
	s_addc_u32 s59, s19, 0
	s_add_i32 s39, s66, s56
	global_load_lds_dwordx4 v[222:223], off
	v_lshl_add_u64 v[226:227], s[58:59], 0, v[130:131]
	s_mov_b32 m0, s39
	v_lshl_add_u64 v[228:229], s[36:37], 0, v[132:133]
	global_load_lds_dwordx4 v[226:227], off
	v_lshl_add_u64 v[226:227], s[58:59], 0, v[134:135]
	s_add_i32 m0, s39, 0x2000
	s_nop 0
	global_load_lds_dwordx4 v[226:227], off
	v_lshl_add_u64 v[226:227], s[36:37], 0, v[128:129]
	s_mov_b32 m0, s57
	s_nop 0
	global_load_lds_dwordx4 v[226:227], off
	s_mov_b32 m0, s68
	s_nop 0
	global_load_lds_dwordx4 v[228:229], off
	s_waitcnt vmcnt(8)
	s_waitcnt lgkmcnt(0)
	s_barrier
; #define PG8_STAGE(bufoff, gbase, voff) do { _Pragma("unroll") for (int _i = 0; _i < 2; ++_i) \
;         __builtin_amdgcn_global_load_lds((const unsigned*)((const char*)(gbase) + (voff)[_i]), (LAS unsigned*)(lds + (bufoff) + ldsw + _i * 8192), 16, 0, 0); } while (0)
; #define PG8_LDA(dst, b, h) do { _Pragma("unroll") for (int m = 0; m < 4; ++m) _Pragma("unroll") for (int k = 0; k < 2; ++k) dst[m][k] = *(const LAS bf16x8*)(lds + PG8_SA(b, h) + aoff + m * 2048 + k * 1024); } while (0)
; #define PG8_LDB(dst, b, h) do { _Pragma("unroll") for (int n = 0; n < 2; ++n) _Pragma("unroll") for (int k = 0; k < 2; ++k) dst[n][k] = *(const LAS bf16x8*)(lds + PG8_SB(b, h) + boff + n * 2048 + k * 1024); } while (0)
; #define PG8_MMA(ai, bj, At, Bt) do { __builtin_amdgcn_s_setprio(1); _Pragma("unroll") for (int m = 0; m < 4; ++m) _Pragma("unroll") for (int n = 0; n < 2; ++n) _Pragma("unroll") for (int k = 0; k < 2; ++k) \
;         acc[ai][bj][m][n] = __builtin_amdgcn_mfma_f32_16x16x32_bf16(Bt[n][k], At[m][k], acc[ai][bj][m][n], 0, 0, 0); __builtin_amdgcn_s_setprio(0); } while (0)
; #define PG8_WAIT_V(n) asm volatile("s_waitcnt vmcnt(" #n ")" ::: "memory")
; #define PG8_WAIT_L(n) asm volatile("s_waitcnt lgkmcnt(" #n ")" ::: "memory")
; #define PG8_BAR __builtin_amdgcn_s_barrier()
; #define PG8_SCHED __builtin_amdgcn_sched_barrier(0)
; template <class Epi, class Sched, bool ALIGN_EPI = true, bool SP2 = true>
; __device__ __forceinline__ void gemm_phase(LAS unsigned char* lds, const int K, const Sched& S, const Epi& E) {
;     ...
;             PG8_WAIT_V(8); PG8_WAIT_L(0); PG8_BAR; PG8_MMA(1, 0, At, B0); PG8_MMA(1, 1, At, B1); PG8_BAR; PG8_SCHED;
;             PG8_LDB(B0, 1, 0); PG8_LDB(B1, 1, 1); PG8_SCHED; PG8_LDA(At, 1, 0); PG8_STAGE(PG8_SA(0, 1), a2 + hstep, voffA);
;             PG8_WAIT_V(8); PG8_WAIT_L(0); PG8_BAR; PG8_MMA(0, 0, At, B0); PG8_MMA(0, 1, At, B1); PG8_BAR; PG8_SCHED;
	s_setprio 1
	s_waitcnt lgkmcnt(0)
	v_mfma_f32_16x16x32_bf16 v[60:63], v[140:143], v[172:175], 0
	v_mfma_f32_16x16x32_bf16 v[56:59], v[148:151], v[172:175], 0
	v_mfma_f32_16x16x32_bf16 v[52:55], v[140:143], v[180:183], 0
	v_mfma_f32_16x16x32_bf16 v[48:51], v[148:151], v[180:183], 0
	v_mfma_f32_16x16x32_bf16 v[36:39], v[140:143], v[188:191], 0
	v_mfma_f32_16x16x32_bf16 v[32:35], v[148:151], v[188:191], 0
	v_mfma_f32_16x16x32_bf16 v[20:23], v[140:143], v[212:215], 0
	v_mfma_f32_16x16x32_bf16 v[16:19], v[148:151], v[212:215], 0
	v_mfma_f32_16x16x32_bf16 v[60:63], v[144:147], v[176:179], v[60:63]
	v_mfma_f32_16x16x32_bf16 v[56:59], v[152:155], v[176:179], v[56:59]
	v_mfma_f32_16x16x32_bf16 v[52:55], v[144:147], v[184:187], v[52:55]
	v_mfma_f32_16x16x32_bf16 v[48:51], v[152:155], v[184:187], v[48:51]
	v_mfma_f32_16x16x32_bf16 v[36:39], v[144:147], v[208:211], v[36:39]
	v_mfma_f32_16x16x32_bf16 v[32:35], v[152:155], v[208:211], v[32:35]
	v_mfma_f32_16x16x32_bf16 v[20:23], v[144:147], v[216:219], v[20:23]
	v_mfma_f32_16x16x32_bf16 v[16:19], v[152:155], v[216:219], v[16:19]
	s_setprio 0
	s_setprio 1
	v_mfma_f32_16x16x32_bf16 v[44:47], v[156:159], v[172:175], 0
	v_mfma_f32_16x16x32_bf16 v[40:43], v[164:167], v[172:175], 0
	v_mfma_f32_16x16x32_bf16 v[28:31], v[156:159], v[180:183], 0
	v_mfma_f32_16x16x32_bf16 v[24:27], v[164:167], v[180:183], 0
	v_mfma_f32_16x16x32_bf16 v[12:15], v[156:159], v[188:191], 0
	v_mfma_f32_16x16x32_bf16 v[8:11], v[164:167], v[188:191], 0
	v_mfma_f32_16x16x32_bf16 v[4:7], v[156:159], v[212:215], 0
	v_mfma_f32_16x16x32_bf16 v[0:3], v[164:167], v[212:215], 0
	v_mfma_f32_16x16x32_bf16 v[44:47], v[160:163], v[176:179], v[44:47]
	v_mfma_f32_16x16x32_bf16 v[40:43], v[168:171], v[176:179], v[40:43]
	v_mfma_f32_16x16x32_bf16 v[28:31], v[160:163], v[184:187], v[28:31]
	v_mfma_f32_16x16x32_bf16 v[24:27], v[168:171], v[184:187], v[24:27]
	v_mfma_f32_16x16x32_bf16 v[12:15], v[160:163], v[208:211], v[12:15]
	v_mfma_f32_16x16x32_bf16 v[8:11], v[168:171], v[208:211], v[8:11]
	v_mfma_f32_16x16x32_bf16 v[4:7], v[160:163], v[216:219], v[4:7]
	v_mfma_f32_16x16x32_bf16 v[0:3], v[168:171], v[216:219], v[0:3]
	s_setprio 0
	s_barrier
	s_add_i32 s39, 0, 0x18000
	s_add_i32 s58, 0, 0x1c000
	v_add_u32_e32 v152, s39, v233
	v_add_u32_e32 v168, s58, v233
	ds_read_b128 v[140:143], v152
	ds_read_b128 v[144:147], v152 offset:1024
	ds_read_b128 v[148:151], v152 offset:2048
	ds_read_b128 v[152:155], v152 offset:3072
	ds_read_b128 v[156:159], v168
	ds_read_b128 v[160:163], v168 offset:1024
	ds_read_b128 v[164:167], v168 offset:2048
	ds_read_b128 v[168:171], v168 offset:3072
	s_add_u32 s36, s36, 0x40000
	s_addc_u32 s37, s37, 0
	s_mov_b32 m0, s69
	v_lshl_add_u64 v[236:237], s[36:37], 0, v[128:129]
	ds_read_b128 v[172:175], v234 offset:32768
	ds_read_b128 v[176:179], v234 offset:33792
	ds_read_b128 v[180:183], v234 offset:34816
	ds_read_b128 v[184:187], v234 offset:35840
	ds_read_b128 v[188:191], v234 offset:36864
	ds_read_b128 v[208:211], v234 offset:37888
	ds_read_b128 v[212:215], v234 offset:38912
	ds_read_b128 v[216:219], v234 offset:39936
	global_load_lds_dwordx4 v[236:237], off
	v_lshl_add_u64 v[236:237], s[36:37], 0, v[132:133]
	s_mov_b32 m0, s80
	s_nop 0
	global_load_lds_dwordx4 v[236:237], off
	s_waitcnt vmcnt(8)
	s_waitcnt lgkmcnt(0)
	s_barrier
	s_setprio 1
	s_waitcnt lgkmcnt(0)
	v_mfma_f32_16x16x32_bf16 v[124:127], v[140:143], v[172:175], v[124:127]
	v_mfma_f32_16x16x32_bf16 v[120:123], v[148:151], v[172:175], v[120:123]
	v_mfma_f32_16x16x32_bf16 v[116:119], v[140:143], v[180:183], v[116:119]
	v_mfma_f32_16x16x32_bf16 v[112:115], v[148:151], v[180:183], v[112:115]
	v_mfma_f32_16x16x32_bf16 v[100:103], v[140:143], v[188:191], v[100:103]
	v_mfma_f32_16x16x32_bf16 v[96:99], v[148:151], v[188:191], v[96:99]
	v_mfma_f32_16x16x32_bf16 v[84:87], v[140:143], v[212:215], v[84:87]
	v_mfma_f32_16x16x32_bf16 v[80:83], v[148:151], v[212:215], v[80:83]
	v_mfma_f32_16x16x32_bf16 v[124:127], v[144:147], v[176:179], v[124:127]
	v_mfma_f32_16x16x32_bf16 v[120:123], v[152:155], v[176:179], v[120:123]
	v_mfma_f32_16x16x32_bf16 v[116:119], v[144:147], v[184:187], v[116:119]
	v_mfma_f32_16x16x32_bf16 v[112:115], v[152:155], v[184:187], v[112:115]
	v_mfma_f32_16x16x32_bf16 v[100:103], v[144:147], v[208:211], v[100:103]
	v_mfma_f32_16x16x32_bf16 v[96:99], v[152:155], v[208:211], v[96:99]
	v_mfma_f32_16x16x32_bf16 v[84:87], v[144:147], v[216:219], v[84:87]
	v_mfma_f32_16x16x32_bf16 v[80:83], v[152:155], v[216:219], v[80:83]
	s_setprio 0
	s_setprio 1
	v_mfma_f32_16x16x32_bf16 v[108:111], v[156:159], v[172:175], v[108:111]
	v_mfma_f32_16x16x32_bf16 v[104:107], v[164:167], v[172:175], v[104:107]
	v_mfma_f32_16x16x32_bf16 v[92:95], v[156:159], v[180:183], v[92:95]
	v_mfma_f32_16x16x32_bf16 v[88:91], v[164:167], v[180:183], v[88:91]
	v_mfma_f32_16x16x32_bf16 v[76:79], v[156:159], v[188:191], v[76:79]
	v_mfma_f32_16x16x32_bf16 v[72:75], v[164:167], v[188:191], v[72:75]
	v_mfma_f32_16x16x32_bf16 v[68:71], v[156:159], v[212:215], v[68:71]
	v_mfma_f32_16x16x32_bf16 v[64:67], v[164:167], v[212:215], v[64:67]
	v_mfma_f32_16x16x32_bf16 v[108:111], v[160:163], v[176:179], v[108:111]
	v_mfma_f32_16x16x32_bf16 v[104:107], v[168:171], v[176:179], v[104:107]
	v_mfma_f32_16x16x32_bf16 v[92:95], v[160:163], v[184:187], v[92:95]
	v_mfma_f32_16x16x32_bf16 v[88:91], v[168:171], v[184:187], v[88:91]
	v_mfma_f32_16x16x32_bf16 v[76:79], v[160:163], v[208:211], v[76:79]
	v_mfma_f32_16x16x32_bf16 v[72:75], v[168:171], v[208:211], v[72:75]
	v_mfma_f32_16x16x32_bf16 v[68:71], v[160:163], v[216:219], v[68:71]
	v_mfma_f32_16x16x32_bf16 v[64:67], v[168:171], v[216:219], v[64:67]
	s_setprio 0
	s_barrier
; #define PG8_STAGE(bufoff, gbase, voff) do { _Pragma("unroll") for (int _i = 0; _i < 2; ++_i) \
;         __builtin_amdgcn_global_load_lds((const unsigned*)((const char*)(gbase) + (voff)[_i]), (LAS unsigned*)(lds + (bufoff) + ldsw + _i * 8192), 16, 0, 0); } while (0)
; #define PG8_LDA(dst, b, h) do { _Pragma("unroll") for (int m = 0; m < 4; ++m) _Pragma("unroll") for (int k = 0; k < 2; ++k) dst[m][k] = *(const LAS bf16x8*)(lds + PG8_SA(b, h) + aoff + m * 2048 + k * 1024); } while (0)
; #define PG8_MMA(ai, bj, At, Bt) do { __builtin_amdgcn_s_setprio(1); _Pragma("unroll") for (int m = 0; m < 4; ++m) _Pragma("unroll") for (int n = 0; n < 2; ++n) _Pragma("unroll") for (int k = 0; k < 2; ++k) \
;         acc[ai][bj][m][n] = __builtin_amdgcn_mfma_f32_16x16x32_bf16(Bt[n][k], At[m][k], acc[ai][bj][m][n], 0, 0, 0); __builtin_amdgcn_s_setprio(0); } while (0)
; #define PG8_WAIT_V(n) asm volatile("s_waitcnt vmcnt(" #n ")" ::: "memory")
; #define PG8_WAIT_L(n) asm volatile("s_waitcnt lgkmcnt(" #n ")" ::: "memory")
; #define PG8_BAR __builtin_amdgcn_s_barrier()
; #define PG8_SCHED __builtin_amdgcn_sched_barrier(0)
; template <class Epi, class Sched, bool ALIGN_EPI = true, bool SP2 = true>
; __device__ __forceinline__ void gemm_phase(LAS unsigned char* lds, const int K, const Sched& S, const Epi& E) {
;     ...
;             PG8_LDA(At, 1, 1); PG8_STAGE(PG8_SB(1, 0), b3, voffB); PG8_STAGE(PG8_SB(1, 1), b3 + hstep, voffB); PG8_STAGE(PG8_SA(1, 0), a3, voffA);
;             PG8_WAIT_V(8); PG8_WAIT_L(0); PG8_BAR; PG8_MMA(1, 0, At, B0); PG8_MMA(1, 1, At, B1); PG8_BAR; PG8_SCHED;
	s_add_i32 s36, s39, s56
	v_lshl_add_u64 v[220:221], v[220:221], 0, s[94:95]
	s_mov_b32 m0, s36
	ds_read_b128 v[172:175], v234 offset:49152
	ds_read_b128 v[176:179], v234 offset:50176
	ds_read_b128 v[180:183], v234 offset:51200
	ds_read_b128 v[184:187], v234 offset:52224
	ds_read_b128 v[188:191], v234 offset:53248
	ds_read_b128 v[208:211], v234 offset:54272
	ds_read_b128 v[212:215], v234 offset:55296
	ds_read_b128 v[216:219], v234 offset:56320
	global_load_lds_dwordx4 v[220:221], off
	s_add_i32 m0, s36, 0x2000
	s_add_u32 s18, s18, 0x40080
	v_lshl_add_u64 v[220:221], v[222:223], 0, s[94:95]
	s_addc_u32 s19, s19, 0
	s_add_i32 s36, s58, s56
	global_load_lds_dwordx4 v[220:221], off
	v_lshl_add_u64 v[220:221], s[18:19], 0, v[130:131]
	s_mov_b32 m0, s36
	s_nop 0
	global_load_lds_dwordx4 v[220:221], off
	v_lshl_add_u64 v[220:221], s[18:19], 0, v[134:135]
	s_add_i32 m0, s36, 0x2000
	s_nop 0
	global_load_lds_dwordx4 v[220:221], off
	v_lshl_add_u64 v[220:221], v[226:227], 0, s[94:95]
	s_mov_b32 m0, s47
	s_nop 0
	global_load_lds_dwordx4 v[220:221], off
	v_lshl_add_u64 v[220:221], v[228:229], 0, s[94:95]
	s_mov_b32 m0, s81
	s_nop 0
	global_load_lds_dwordx4 v[220:221], off
	s_waitcnt vmcnt(8)
	s_waitcnt lgkmcnt(0)
	s_barrier
	s_setprio 1
	s_waitcnt lgkmcnt(0)
	v_mfma_f32_16x16x32_bf16 v[60:63], v[140:143], v[172:175], v[60:63]
	v_mfma_f32_16x16x32_bf16 v[56:59], v[148:151], v[172:175], v[56:59]
	v_mfma_f32_16x16x32_bf16 v[52:55], v[140:143], v[180:183], v[52:55]
	v_mfma_f32_16x16x32_bf16 v[48:51], v[148:151], v[180:183], v[48:51]
	v_mfma_f32_16x16x32_bf16 v[36:39], v[140:143], v[188:191], v[36:39]
	v_mfma_f32_16x16x32_bf16 v[32:35], v[148:151], v[188:191], v[32:35]
	v_mfma_f32_16x16x32_bf16 v[20:23], v[140:143], v[212:215], v[20:23]
	v_mfma_f32_16x16x32_bf16 v[16:19], v[148:151], v[212:215], v[16:19]
	v_mfma_f32_16x16x32_bf16 v[60:63], v[144:147], v[176:179], v[60:63]
	v_mfma_f32_16x16x32_bf16 v[56:59], v[152:155], v[176:179], v[56:59]
	v_mfma_f32_16x16x32_bf16 v[52:55], v[144:147], v[184:187], v[52:55]
	v_mfma_f32_16x16x32_bf16 v[48:51], v[152:155], v[184:187], v[48:51]
	v_mfma_f32_16x16x32_bf16 v[36:39], v[144:147], v[208:211], v[36:39]
	v_mfma_f32_16x16x32_bf16 v[32:35], v[152:155], v[208:211], v[32:35]
	v_mfma_f32_16x16x32_bf16 v[20:23], v[144:147], v[216:219], v[20:23]
	v_mfma_f32_16x16x32_bf16 v[16:19], v[152:155], v[216:219], v[16:19]
	s_setprio 0
	s_setprio 1
	v_mfma_f32_16x16x32_bf16 v[44:47], v[156:159], v[172:175], v[44:47]
	v_mfma_f32_16x16x32_bf16 v[40:43], v[164:167], v[172:175], v[40:43]
	v_mfma_f32_16x16x32_bf16 v[28:31], v[156:159], v[180:183], v[28:31]
	v_mfma_f32_16x16x32_bf16 v[24:27], v[164:167], v[180:183], v[24:27]
	v_mfma_f32_16x16x32_bf16 v[12:15], v[156:159], v[188:191], v[12:15]
	v_mfma_f32_16x16x32_bf16 v[8:11], v[164:167], v[188:191], v[8:11]
	v_mfma_f32_16x16x32_bf16 v[4:7], v[156:159], v[212:215], v[4:7]
	v_mfma_f32_16x16x32_bf16 v[0:3], v[164:167], v[212:215], v[0:3]
	v_mfma_f32_16x16x32_bf16 v[44:47], v[160:163], v[176:179], v[44:47]
	v_mfma_f32_16x16x32_bf16 v[40:43], v[168:171], v[176:179], v[40:43]
	v_mfma_f32_16x16x32_bf16 v[28:31], v[160:163], v[184:187], v[28:31]
	v_mfma_f32_16x16x32_bf16 v[24:27], v[168:171], v[184:187], v[24:27]
	v_mfma_f32_16x16x32_bf16 v[12:15], v[160:163], v[208:211], v[12:15]
	v_mfma_f32_16x16x32_bf16 v[8:11], v[168:171], v[208:211], v[8:11]
	v_mfma_f32_16x16x32_bf16 v[4:7], v[160:163], v[216:219], v[4:7]
	v_mfma_f32_16x16x32_bf16 v[0:3], v[168:171], v[216:219], v[0:3]
	s_setprio 0
	s_barrier
	s_add_i32 s38, s38, 2
	s_add_u32 s0, s0, 0x100
	s_addc_u32 s1, s1, 0
	s_add_u32 s11, s11, 0x100
	s_addc_u32 s15, s15, 0
	s_cmp_gt_u32 s38, 13

; #define PG8_STAGE(bufoff, gbase, voff) do { _Pragma("unroll") for (int _i = 0; _i < 2; ++_i) \
;         __builtin_amdgcn_global_load_lds((const unsigned*)((const char*)(gbase) + (voff)[_i]), (LAS unsigned*)(lds + (bufoff) + ldsw + _i * 8192), 16, 0, 0); } while (0)
; #define PG8_LDA(dst, b, h) do { _Pragma("unroll") for (int m = 0; m < 4; ++m) _Pragma("unroll") for (int k = 0; k < 2; ++k) dst[m][k] = *(const LAS bf16x8*)(lds + PG8_SA(b, h) + aoff + m * 2048 + k * 1024); } while (0)
; #define PG8_LDB(dst, b, h) do { _Pragma("unroll") for (int n = 0; n < 2; ++n) _Pragma("unroll") for (int k = 0; k < 2; ++k) dst[n][k] = *(const LAS bf16x8*)(lds + PG8_SB(b, h) + boff + n * 2048 + k * 1024); } while (0)
; #define PG8_MMA(ai, bj, At, Bt) do { __builtin_amdgcn_s_setprio(1); _Pragma("unroll") for (int m = 0; m < 4; ++m) _Pragma("unroll") for (int n = 0; n < 2; ++n) _Pragma("unroll") for (int k = 0; k < 2; ++k) \
;         acc[ai][bj][m][n] = __builtin_amdgcn_mfma_f32_16x16x32_bf16(Bt[n][k], At[m][k], acc[ai][bj][m][n], 0, 0, 0); __builtin_amdgcn_s_setprio(0); } while (0)
; template <class Epi, class Sched, bool ALIGN_EPI = true, bool SP2 = true>
; __device__ __forceinline__ void gemm_phase(LAS unsigned char* lds, const int K, const Sched& S, const Epi& E) {
;     ...
;     f32x4 acc[2][2][4][2];
; #pragma unroll
;     for (int a = 0; a < 2; ++a)
; #pragma unroll
;         for (int b = 0; b < 2; ++b)
; #pragma unroll
;             for (int m = 0; m < 4; ++m)
; #pragma unroll
;                 for (int n = 0; n < 2; ++n) acc[a][b][m][n] = (f32x4){0.f, 0.f, 0.f, 0.f};
;     ...
;         for (int t = 0; t < nt; t += 2) {
;             const bool last = (t == nt - 2);
;             const char* a1 = cA + (size_t)(t + 1) * kstep;
;             const char* a2 = last ? nA : cA + (size_t)(t + 2) * kstep; const char* b2 = last ? nB : cB + (size_t)(t + 2) * kstep;
;             const char* a3 = a2 + kstep; const char* b3 = b2 + kstep;
;             if constexpr (SP2) {
;             PG8_LDB(B0, 0, 0); PG8_LDB(B1, 0, 1); PG8_SCHED; PG8_LDA(At, 0, 0); PG8_STAGE(PG8_SA(1, 1), a1 + hstep, voffA);
;             PG8_WAIT_V(8); PG8_WAIT_L(0); PG8_BAR; PG8_MMA(0, 0, At, B0); PG8_MMA(0, 1, At, B1); PG8_BAR; PG8_SCHED;
;             PG8_LDA(At, 0, 1); PG8_STAGE(PG8_SB(0, 0), b2, voffB); PG8_STAGE(PG8_SB(0, 1), b2 + hstep, voffB); PG8_STAGE(PG8_SA(0, 0), a2, voffA);
.LBB0_926:
	s_add_i32 s15, s37, -2
	s_add_u32 s38, s38, 0x40080
	s_addc_u32 s39, s39, 0
	s_add_u32 s69, s40, 0x100
	s_addc_u32 s81, s41, 0
	s_mov_b32 s40, 0
	s_add_i32 vcc_lo, s40, 2
	s_add_u32 s41, s38, 0xfffc0080
	s_addc_u32 s42, s39, -1
	s_add_i32 s78, 0, 0x10000
	s_cmp_eq_u32 s15, s40
	s_cselect_b32 s43, s17, s42
	s_cselect_b32 s42, s16, s41
	s_cselect_b32 s41, s19, s81
	s_cselect_b32 s40, s18, s69
	s_add_i32 vcc_hi, 0, 0x14000
	v_add_u32_e32 v140, s78, v164
	v_add_u32_e32 v170, vcc_hi, v164
	ds_read_b128 v[128:131], v140
	ds_read_b128 v[132:135], v140 offset:1024
	ds_read_b128 v[136:139], v140 offset:2048
	ds_read_b128 v[140:143], v140 offset:3072
	ds_read_b128 v[154:157], v170
	ds_read_b128 v[158:161], v170 offset:1024
	ds_read_b128 v[166:169], v170 offset:2048
	ds_read_b128 v[170:173], v170 offset:3072
	v_lshl_add_u64 v[190:191], s[38:39], 0, v[150:151]
	s_add_i32 m0, s57, 0xc000
	ds_read_b128 v[174:177], v165
	ds_read_b128 v[178:181], v165 offset:1024
	ds_read_b128 v[182:185], v165 offset:2048
	ds_read_b128 v[186:189], v165 offset:3072
	ds_read_b128 v[208:211], v165 offset:4096
	ds_read_b128 v[212:215], v165 offset:5120
	ds_read_b128 v[216:219], v165 offset:6144
	ds_read_b128 v[220:223], v165 offset:7168
	global_load_lds_dwordx4 v[190:191], off
	v_lshl_add_u64 v[190:191], s[38:39], 0, v[152:153]
	s_add_i32 m0, s57, 0xe000
	s_nop 0
	global_load_lds_dwordx4 v[190:191], off
	s_waitcnt vmcnt(8)
	s_waitcnt lgkmcnt(0)
	s_barrier
	s_setprio 1
	s_waitcnt lgkmcnt(0)
	v_mfma_f32_16x16x32_bf16 v[124:127], v[128:131], v[174:177], 0
	v_mfma_f32_16x16x32_bf16 v[120:123], v[136:139], v[174:177], 0
	v_mfma_f32_16x16x32_bf16 v[116:119], v[128:131], v[182:185], 0
	v_mfma_f32_16x16x32_bf16 v[112:115], v[136:139], v[182:185], 0
	v_mfma_f32_16x16x32_bf16 v[104:107], v[128:131], v[208:211], 0
	v_mfma_f32_16x16x32_bf16 v[96:99], v[136:139], v[208:211], 0
	v_mfma_f32_16x16x32_bf16 v[88:91], v[128:131], v[216:219], 0
	v_mfma_f32_16x16x32_bf16 v[80:83], v[136:139], v[216:219], 0
	v_mfma_f32_16x16x32_bf16 v[124:127], v[132:135], v[178:181], v[124:127]
	v_mfma_f32_16x16x32_bf16 v[120:123], v[140:143], v[178:181], v[120:123]
	v_mfma_f32_16x16x32_bf16 v[116:119], v[132:135], v[186:189], v[116:119]
	v_mfma_f32_16x16x32_bf16 v[112:115], v[140:143], v[186:189], v[112:115]
	v_mfma_f32_16x16x32_bf16 v[104:107], v[132:135], v[212:215], v[104:107]
	v_mfma_f32_16x16x32_bf16 v[96:99], v[140:143], v[212:215], v[96:99]
	v_mfma_f32_16x16x32_bf16 v[88:91], v[132:135], v[220:223], v[88:91]
	v_mfma_f32_16x16x32_bf16 v[80:83], v[140:143], v[220:223], v[80:83]
	s_setprio 0
	s_setprio 1
	v_mfma_f32_16x16x32_bf16 v[108:111], v[154:157], v[174:177], 0
	v_mfma_f32_16x16x32_bf16 v[100:103], v[166:169], v[174:177], 0
	v_mfma_f32_16x16x32_bf16 v[92:95], v[154:157], v[182:185], 0
	v_mfma_f32_16x16x32_bf16 v[84:87], v[166:169], v[182:185], 0
	v_mfma_f32_16x16x32_bf16 v[76:79], v[154:157], v[208:211], 0
	v_mfma_f32_16x16x32_bf16 v[72:75], v[166:169], v[208:211], 0
	v_mfma_f32_16x16x32_bf16 v[68:71], v[154:157], v[216:219], 0
	v_mfma_f32_16x16x32_bf16 v[64:67], v[166:169], v[216:219], 0
	v_mfma_f32_16x16x32_bf16 v[108:111], v[158:161], v[178:181], v[108:111]
	v_mfma_f32_16x16x32_bf16 v[100:103], v[170:173], v[178:181], v[100:103]
	v_mfma_f32_16x16x32_bf16 v[92:95], v[158:161], v[186:189], v[92:95]
	v_mfma_f32_16x16x32_bf16 v[84:87], v[170:173], v[186:189], v[84:87]
	v_mfma_f32_16x16x32_bf16 v[76:79], v[158:161], v[212:215], v[76:79]
	v_mfma_f32_16x16x32_bf16 v[72:75], v[170:173], v[212:215], v[72:75]
	v_mfma_f32_16x16x32_bf16 v[68:71], v[158:161], v[220:223], v[68:71]
	v_mfma_f32_16x16x32_bf16 v[64:67], v[170:173], v[220:223], v[64:67]
	s_setprio 0
	s_barrier
	s_add_i32 s78, s78, s56
	v_lshl_add_u64 v[190:191], s[40:41], 0, v[194:195]
	s_mov_b32 m0, s78
	ds_read_b128 v[174:177], v165 offset:16384
	ds_read_b128 v[178:181], v165 offset:17408
	ds_read_b128 v[182:185], v165 offset:18432
	ds_read_b128 v[186:189], v165 offset:19456
	ds_read_b128 v[208:211], v165 offset:20480
	ds_read_b128 v[212:215], v165 offset:21504
	ds_read_b128 v[216:219], v165 offset:22528
	ds_read_b128 v[220:223], v165 offset:23552
	global_load_lds_dwordx4 v[190:191], off
	s_add_i32 m0, s78, 0x2000
	s_add_u32 s78, s40, 0x40000
	v_lshl_add_u64 v[226:227], s[40:41], 0, v[148:149]
	s_addc_u32 s79, s41, 0
	s_add_i32 vcc_hi, vcc_hi, s56
	global_load_lds_dwordx4 v[226:227], off
	v_lshl_add_u64 v[228:229], s[78:79], 0, v[194:195]
	s_mov_b32 m0, vcc_hi
	v_lshl_add_u64 v[230:231], s[42:43], 0, v[146:147]
	global_load_lds_dwordx4 v[228:229], off
	v_lshl_add_u64 v[228:229], s[78:79], 0, v[148:149]
	s_add_i32 m0, vcc_hi, 0x2000
	s_nop 0
	global_load_lds_dwordx4 v[228:229], off
	v_lshl_add_u64 v[228:229], s[42:43], 0, v[144:145]
	s_mov_b32 m0, s57
	s_nop 0
	global_load_lds_dwordx4 v[228:229], off
	s_mov_b32 m0, s59
	s_nop 0
	global_load_lds_dwordx4 v[230:231], off
	s_waitcnt vmcnt(8)
	s_waitcnt lgkmcnt(0)
	s_barrier
; #define PG8_STAGE(bufoff, gbase, voff) do { _Pragma("unroll") for (int _i = 0; _i < 2; ++_i) \
;         __builtin_amdgcn_global_load_lds((const unsigned*)((const char*)(gbase) + (voff)[_i]), (LAS unsigned*)(lds + (bufoff) + ldsw + _i * 8192), 16, 0, 0); } while (0)
; #define PG8_LDA(dst, b, h) do { _Pragma("unroll") for (int m = 0; m < 4; ++m) _Pragma("unroll") for (int k = 0; k < 2; ++k) dst[m][k] = *(const LAS bf16x8*)(lds + PG8_SA(b, h) + aoff + m * 2048 + k * 1024); } while (0)
; #define PG8_LDB(dst, b, h) do { _Pragma("unroll") for (int n = 0; n < 2; ++n) _Pragma("unroll") for (int k = 0; k < 2; ++k) dst[n][k] = *(const LAS bf16x8*)(lds + PG8_SB(b, h) + boff + n * 2048 + k * 1024); } while (0)
; #define PG8_MMA(ai, bj, At, Bt) do { __builtin_amdgcn_s_setprio(1); _Pragma("unroll") for (int m = 0; m < 4; ++m) _Pragma("unroll") for (int n = 0; n < 2; ++n) _Pragma("unroll") for (int k = 0; k < 2; ++k) \
;         acc[ai][bj][m][n] = __builtin_amdgcn_mfma_f32_16x16x32_bf16(Bt[n][k], At[m][k], acc[ai][bj][m][n], 0, 0, 0); __builtin_amdgcn_s_setprio(0); } while (0)
; #define PG8_WAIT_V(n) asm volatile("s_waitcnt vmcnt(" #n ")" ::: "memory")
; #define PG8_WAIT_L(n) asm volatile("s_waitcnt lgkmcnt(" #n ")" ::: "memory")
; #define PG8_BAR __builtin_amdgcn_s_barrier()
; #define PG8_SCHED __builtin_amdgcn_sched_barrier(0)
; template <class Epi, class Sched, bool ALIGN_EPI = true, bool SP2 = true>
; __device__ __forceinline__ void gemm_phase(LAS unsigned char* lds, const int K, const Sched& S, const Epi& E) {
;     ...
;             PG8_WAIT_V(8); PG8_WAIT_L(0); PG8_BAR; PG8_MMA(1, 0, At, B0); PG8_MMA(1, 1, At, B1); PG8_BAR; PG8_SCHED;
;             PG8_LDB(B0, 1, 0); PG8_LDB(B1, 1, 1); PG8_SCHED; PG8_LDA(At, 1, 0); PG8_STAGE(PG8_SA(0, 1), a2 + hstep, voffA);
;             PG8_WAIT_V(8); PG8_WAIT_L(0); PG8_BAR; PG8_MMA(0, 0, At, B0); PG8_MMA(0, 1, At, B1); PG8_BAR; PG8_SCHED;
	s_setprio 1
	s_waitcnt lgkmcnt(0)
	v_mfma_f32_16x16x32_bf16 v[60:63], v[128:131], v[174:177], 0
	v_mfma_f32_16x16x32_bf16 v[56:59], v[136:139], v[174:177], 0
	v_mfma_f32_16x16x32_bf16 v[52:55], v[128:131], v[182:185], 0
	v_mfma_f32_16x16x32_bf16 v[48:51], v[136:139], v[182:185], 0
	v_mfma_f32_16x16x32_bf16 v[40:43], v[128:131], v[208:211], 0
	v_mfma_f32_16x16x32_bf16 v[32:35], v[136:139], v[208:211], 0
	v_mfma_f32_16x16x32_bf16 v[24:27], v[128:131], v[216:219], 0
	v_mfma_f32_16x16x32_bf16 v[16:19], v[136:139], v[216:219], 0
	v_mfma_f32_16x16x32_bf16 v[60:63], v[132:135], v[178:181], v[60:63]
	v_mfma_f32_16x16x32_bf16 v[56:59], v[140:143], v[178:181], v[56:59]
	v_mfma_f32_16x16x32_bf16 v[52:55], v[132:135], v[186:189], v[52:55]
	v_mfma_f32_16x16x32_bf16 v[48:51], v[140:143], v[186:189], v[48:51]
	v_mfma_f32_16x16x32_bf16 v[40:43], v[132:135], v[212:215], v[40:43]
	v_mfma_f32_16x16x32_bf16 v[32:35], v[140:143], v[212:215], v[32:35]
	v_mfma_f32_16x16x32_bf16 v[24:27], v[132:135], v[220:223], v[24:27]
	v_mfma_f32_16x16x32_bf16 v[16:19], v[140:143], v[220:223], v[16:19]
	s_setprio 0
	s_setprio 1
	v_mfma_f32_16x16x32_bf16 v[44:47], v[154:157], v[174:177], 0
	v_mfma_f32_16x16x32_bf16 v[36:39], v[166:169], v[174:177], 0
	v_mfma_f32_16x16x32_bf16 v[28:31], v[154:157], v[182:185], 0
	v_mfma_f32_16x16x32_bf16 v[20:23], v[166:169], v[182:185], 0
	v_mfma_f32_16x16x32_bf16 v[12:15], v[154:157], v[208:211], 0
	v_mfma_f32_16x16x32_bf16 v[8:11], v[166:169], v[208:211], 0
	v_mfma_f32_16x16x32_bf16 v[4:7], v[154:157], v[216:219], 0
	v_mfma_f32_16x16x32_bf16 v[0:3], v[166:169], v[216:219], 0
	v_mfma_f32_16x16x32_bf16 v[44:47], v[158:161], v[178:181], v[44:47]
	v_mfma_f32_16x16x32_bf16 v[36:39], v[170:173], v[178:181], v[36:39]
	v_mfma_f32_16x16x32_bf16 v[28:31], v[158:161], v[186:189], v[28:31]
	v_mfma_f32_16x16x32_bf16 v[20:23], v[170:173], v[186:189], v[20:23]
	v_mfma_f32_16x16x32_bf16 v[12:15], v[158:161], v[212:215], v[12:15]
	v_mfma_f32_16x16x32_bf16 v[8:11], v[170:173], v[212:215], v[8:11]
	v_mfma_f32_16x16x32_bf16 v[4:7], v[158:161], v[220:223], v[4:7]
	v_mfma_f32_16x16x32_bf16 v[0:3], v[170:173], v[220:223], v[0:3]
	s_setprio 0
	s_barrier
	s_add_i32 s78, 0, 0x18000
	s_add_i32 s79, 0, 0x1c000
	v_add_u32_e32 v140, s78, v164
	v_add_u32_e32 v170, s79, v164
	ds_read_b128 v[128:131], v140
	ds_read_b128 v[132:135], v140 offset:1024
	ds_read_b128 v[136:139], v140 offset:2048
	ds_read_b128 v[140:143], v140 offset:3072
	ds_read_b128 v[154:157], v170
	ds_read_b128 v[158:161], v170 offset:1024
	ds_read_b128 v[166:169], v170 offset:2048
	ds_read_b128 v[170:173], v170 offset:3072
	s_add_u32 s42, s42, 0x40000
	s_addc_u32 s43, s43, 0
	s_mov_b32 m0, s66
	v_lshl_add_u64 v[232:233], s[42:43], 0, v[144:145]
	ds_read_b128 v[174:177], v165 offset:32768
	ds_read_b128 v[178:181], v165 offset:33792
	ds_read_b128 v[182:185], v165 offset:34816
	ds_read_b128 v[186:189], v165 offset:35840
	ds_read_b128 v[208:211], v165 offset:36864
	ds_read_b128 v[212:215], v165 offset:37888
	ds_read_b128 v[216:219], v165 offset:38912
	ds_read_b128 v[220:223], v165 offset:39936
	global_load_lds_dwordx4 v[232:233], off
	v_lshl_add_u64 v[232:233], s[42:43], 0, v[146:147]
	s_mov_b32 m0, s67
	s_nop 0
	global_load_lds_dwordx4 v[232:233], off
	s_waitcnt vmcnt(8)
	s_waitcnt lgkmcnt(0)
	s_barrier
	s_setprio 1
	s_waitcnt lgkmcnt(0)
	v_mfma_f32_16x16x32_bf16 v[124:127], v[128:131], v[174:177], v[124:127]
	v_mfma_f32_16x16x32_bf16 v[120:123], v[136:139], v[174:177], v[120:123]
	v_mfma_f32_16x16x32_bf16 v[116:119], v[128:131], v[182:185], v[116:119]
	v_mfma_f32_16x16x32_bf16 v[112:115], v[136:139], v[182:185], v[112:115]
	v_mfma_f32_16x16x32_bf16 v[104:107], v[128:131], v[208:211], v[104:107]
	v_mfma_f32_16x16x32_bf16 v[96:99], v[136:139], v[208:211], v[96:99]
	v_mfma_f32_16x16x32_bf16 v[88:91], v[128:131], v[216:219], v[88:91]
	v_mfma_f32_16x16x32_bf16 v[80:83], v[136:139], v[216:219], v[80:83]
	v_mfma_f32_16x16x32_bf16 v[124:127], v[132:135], v[178:181], v[124:127]
	v_mfma_f32_16x16x32_bf16 v[120:123], v[140:143], v[178:181], v[120:123]
	v_mfma_f32_16x16x32_bf16 v[116:119], v[132:135], v[186:189], v[116:119]
	v_mfma_f32_16x16x32_bf16 v[112:115], v[140:143], v[186:189], v[112:115]
	v_mfma_f32_16x16x32_bf16 v[104:107], v[132:135], v[212:215], v[104:107]
	v_mfma_f32_16x16x32_bf16 v[96:99], v[140:143], v[212:215], v[96:99]
	v_mfma_f32_16x16x32_bf16 v[88:91], v[132:135], v[220:223], v[88:91]
	v_mfma_f32_16x16x32_bf16 v[80:83], v[140:143], v[220:223], v[80:83]
	s_setprio 0
	s_setprio 1
	v_mfma_f32_16x16x32_bf16 v[108:111], v[154:157], v[174:177], v[108:111]
	v_mfma_f32_16x16x32_bf16 v[100:103], v[166:169], v[174:177], v[100:103]
	v_mfma_f32_16x16x32_bf16 v[92:95], v[154:157], v[182:185], v[92:95]
	v_mfma_f32_16x16x32_bf16 v[84:87], v[166:169], v[182:185], v[84:87]
	v_mfma_f32_16x16x32_bf16 v[76:79], v[154:157], v[208:211], v[76:79]
	v_mfma_f32_16x16x32_bf16 v[72:75], v[166:169], v[208:211], v[72:75]
	v_mfma_f32_16x16x32_bf16 v[68:71], v[154:157], v[216:219], v[68:71]
	v_mfma_f32_16x16x32_bf16 v[64:67], v[166:169], v[216:219], v[64:67]
	v_mfma_f32_16x16x32_bf16 v[108:111], v[158:161], v[178:181], v[108:111]
	v_mfma_f32_16x16x32_bf16 v[100:103], v[170:173], v[178:181], v[100:103]
	v_mfma_f32_16x16x32_bf16 v[92:95], v[158:161], v[186:189], v[92:95]
	v_mfma_f32_16x16x32_bf16 v[84:87], v[170:173], v[186:189], v[84:87]
	v_mfma_f32_16x16x32_bf16 v[76:79], v[158:161], v[212:215], v[76:79]
	v_mfma_f32_16x16x32_bf16 v[72:75], v[170:173], v[212:215], v[72:75]
	v_mfma_f32_16x16x32_bf16 v[68:71], v[158:161], v[220:223], v[68:71]
	v_mfma_f32_16x16x32_bf16 v[64:67], v[170:173], v[220:223], v[64:67]
	s_setprio 0
	s_barrier
; #define PG8_STAGE(bufoff, gbase, voff) do { _Pragma("unroll") for (int _i = 0; _i < 2; ++_i) \
;         __builtin_amdgcn_global_load_lds((const unsigned*)((const char*)(gbase) + (voff)[_i]), (LAS unsigned*)(lds + (bufoff) + ldsw + _i * 8192), 16, 0, 0); } while (0)
; #define PG8_LDA(dst, b, h) do { _Pragma("unroll") for (int m = 0; m < 4; ++m) _Pragma("unroll") for (int k = 0; k < 2; ++k) dst[m][k] = *(const LAS bf16x8*)(lds + PG8_SA(b, h) + aoff + m * 2048 + k * 1024); } while (0)
; #define PG8_MMA(ai, bj, At, Bt) do { __builtin_amdgcn_s_setprio(1); _Pragma("unroll") for (int m = 0; m < 4; ++m) _Pragma("unroll") for (int n = 0; n < 2; ++n) _Pragma("unroll") for (int k = 0; k < 2; ++k) \
;         acc[ai][bj][m][n] = __builtin_amdgcn_mfma_f32_16x16x32_bf16(Bt[n][k], At[m][k], acc[ai][bj][m][n], 0, 0, 0); __builtin_amdgcn_s_setprio(0); } while (0)
; #define PG8_WAIT_V(n) asm volatile("s_waitcnt vmcnt(" #n ")" ::: "memory")
; #define PG8_WAIT_L(n) asm volatile("s_waitcnt lgkmcnt(" #n ")" ::: "memory")
; #define PG8_BAR __builtin_amdgcn_s_barrier()
; #define PG8_SCHED __builtin_amdgcn_sched_barrier(0)
; template <class Epi, class Sched, bool ALIGN_EPI = true, bool SP2 = true>
; __device__ __forceinline__ void gemm_phase(LAS unsigned char* lds, const int K, const Sched& S, const Epi& E) {
;     ...
;             PG8_LDA(At, 1, 1); PG8_STAGE(PG8_SB(1, 0), b3, voffB); PG8_STAGE(PG8_SB(1, 1), b3 + hstep, voffB); PG8_STAGE(PG8_SA(1, 0), a3, voffA);
;             PG8_WAIT_V(8); PG8_WAIT_L(0); PG8_BAR; PG8_MMA(1, 0, At, B0); PG8_MMA(1, 1, At, B1); PG8_BAR; PG8_SCHED;
	s_add_i32 s42, s78, s56
	v_lshl_add_u64 v[190:191], v[190:191], 0, s[94:95]
	s_mov_b32 m0, s42
	ds_read_b128 v[174:177], v165 offset:49152
	ds_read_b128 v[178:181], v165 offset:50176
	ds_read_b128 v[182:185], v165 offset:51200
	ds_read_b128 v[186:189], v165 offset:52224
	ds_read_b128 v[208:211], v165 offset:53248
	ds_read_b128 v[212:215], v165 offset:54272
	ds_read_b128 v[216:219], v165 offset:55296
	ds_read_b128 v[220:223], v165 offset:56320
	global_load_lds_dwordx4 v[190:191], off
	s_add_i32 m0, s42, 0x2000
	s_add_u32 s40, s40, 0x40080
	v_lshl_add_u64 v[190:191], v[226:227], 0, s[94:95]
	s_addc_u32 s41, s41, 0
	s_add_i32 s42, s79, s56
	global_load_lds_dwordx4 v[190:191], off
	v_lshl_add_u64 v[190:191], s[40:41], 0, v[194:195]
	s_mov_b32 m0, s42
	s_nop 0
	global_load_lds_dwordx4 v[190:191], off
	v_lshl_add_u64 v[190:191], s[40:41], 0, v[148:149]
	s_add_i32 m0, s42, 0x2000
	s_nop 0
	global_load_lds_dwordx4 v[190:191], off
	v_lshl_add_u64 v[190:191], v[228:229], 0, s[94:95]
	s_mov_b32 m0, s74
	s_nop 0
	global_load_lds_dwordx4 v[190:191], off
	v_lshl_add_u64 v[190:191], v[230:231], 0, s[94:95]
	s_mov_b32 m0, s75
	s_nop 0
	global_load_lds_dwordx4 v[190:191], off
	s_waitcnt vmcnt(8)
	s_waitcnt lgkmcnt(0)
	s_barrier
	s_setprio 1
	s_waitcnt lgkmcnt(0)
	v_mfma_f32_16x16x32_bf16 v[60:63], v[128:131], v[174:177], v[60:63]
	v_mfma_f32_16x16x32_bf16 v[56:59], v[136:139], v[174:177], v[56:59]
	v_mfma_f32_16x16x32_bf16 v[52:55], v[128:131], v[182:185], v[52:55]
	v_mfma_f32_16x16x32_bf16 v[48:51], v[136:139], v[182:185], v[48:51]
	v_mfma_f32_16x16x32_bf16 v[40:43], v[128:131], v[208:211], v[40:43]
	v_mfma_f32_16x16x32_bf16 v[32:35], v[136:139], v[208:211], v[32:35]
	v_mfma_f32_16x16x32_bf16 v[24:27], v[128:131], v[216:219], v[24:27]
	v_mfma_f32_16x16x32_bf16 v[16:19], v[136:139], v[216:219], v[16:19]
	v_mfma_f32_16x16x32_bf16 v[60:63], v[132:135], v[178:181], v[60:63]
	v_mfma_f32_16x16x32_bf16 v[56:59], v[140:143], v[178:181], v[56:59]
	v_mfma_f32_16x16x32_bf16 v[52:55], v[132:135], v[186:189], v[52:55]
	v_mfma_f32_16x16x32_bf16 v[48:51], v[140:143], v[186:189], v[48:51]
	v_mfma_f32_16x16x32_bf16 v[40:43], v[132:135], v[212:215], v[40:43]
	v_mfma_f32_16x16x32_bf16 v[32:35], v[140:143], v[212:215], v[32:35]
	v_mfma_f32_16x16x32_bf16 v[24:27], v[132:135], v[220:223], v[24:27]
	v_mfma_f32_16x16x32_bf16 v[16:19], v[140:143], v[220:223], v[16:19]
	s_setprio 0
	s_setprio 1
	v_mfma_f32_16x16x32_bf16 v[44:47], v[154:157], v[174:177], v[44:47]
	v_mfma_f32_16x16x32_bf16 v[36:39], v[166:169], v[174:177], v[36:39]
	v_mfma_f32_16x16x32_bf16 v[28:31], v[154:157], v[182:185], v[28:31]
	v_mfma_f32_16x16x32_bf16 v[20:23], v[166:169], v[182:185], v[20:23]
	v_mfma_f32_16x16x32_bf16 v[12:15], v[154:157], v[208:211], v[12:15]
	v_mfma_f32_16x16x32_bf16 v[8:11], v[166:169], v[208:211], v[8:11]
	v_mfma_f32_16x16x32_bf16 v[4:7], v[154:157], v[216:219], v[4:7]
	v_mfma_f32_16x16x32_bf16 v[0:3], v[166:169], v[216:219], v[0:3]
	v_mfma_f32_16x16x32_bf16 v[44:47], v[158:161], v[178:181], v[44:47]
	v_mfma_f32_16x16x32_bf16 v[36:39], v[170:173], v[178:181], v[36:39]
	v_mfma_f32_16x16x32_bf16 v[28:31], v[158:161], v[186:189], v[28:31]
	v_mfma_f32_16x16x32_bf16 v[20:23], v[170:173], v[186:189], v[20:23]
	v_mfma_f32_16x16x32_bf16 v[12:15], v[158:161], v[212:215], v[12:15]
	v_mfma_f32_16x16x32_bf16 v[8:11], v[170:173], v[212:215], v[8:11]
	v_mfma_f32_16x16x32_bf16 v[4:7], v[158:161], v[220:223], v[4:7]
	v_mfma_f32_16x16x32_bf16 v[0:3], v[170:173], v[220:223], v[0:3]
	s_setprio 0
	s_barrier
	s_add_u32 s38, s38, 0x100
	s_addc_u32 s39, s39, 0
	s_add_u32 s69, s69, 0x100
	s_addc_u32 s81, s81, 0
	s_cmp_ge_i32 vcc_lo, s37
	s_mov_b32 s40, vcc_lo

; #define PG8_STAGE(bufoff, gbase, voff) do { _Pragma("unroll") for (int _i = 0; _i < 2; ++_i) \
;         __builtin_amdgcn_global_load_lds((const unsigned*)((const char*)(gbase) + (voff)[_i]), (LAS unsigned*)(lds + (bufoff) + ldsw + _i * 8192), 16, 0, 0); } while (0)
; #define PG8_LDA(dst, b, h) do { _Pragma("unroll") for (int m = 0; m < 4; ++m) _Pragma("unroll") for (int k = 0; k < 2; ++k) dst[m][k] = *(const LAS bf16x8*)(lds + PG8_SA(b, h) + aoff + m * 2048 + k * 1024); } while (0)
; #define PG8_LDB(dst, b, h) do { _Pragma("unroll") for (int n = 0; n < 2; ++n) _Pragma("unroll") for (int k = 0; k < 2; ++k) dst[n][k] = *(const LAS bf16x8*)(lds + PG8_SB(b, h) + boff + n * 2048 + k * 1024); } while (0)
; #define PG8_MMA(ai, bj, At, Bt) do { __builtin_amdgcn_s_setprio(1); _Pragma("unroll") for (int m = 0; m < 4; ++m) _Pragma("unroll") for (int n = 0; n < 2; ++n) _Pragma("unroll") for (int k = 0; k < 2; ++k) \
;         acc[ai][bj][m][n] = __builtin_amdgcn_mfma_f32_16x16x32_bf16(Bt[n][k], At[m][k], acc[ai][bj][m][n], 0, 0, 0); __builtin_amdgcn_s_setprio(0); } while (0)
; template <class Epi, class Sched, bool ALIGN_EPI = true, bool SP2 = true>
; __device__ __forceinline__ void gemm_phase(LAS unsigned char* lds, const int K, const Sched& S, const Epi& E) {
;     ...
;     f32x4 acc[2][2][4][2];
; #pragma unroll
;     for (int a = 0; a < 2; ++a)
; #pragma unroll
;         for (int b = 0; b < 2; ++b)
; #pragma unroll
;             for (int m = 0; m < 4; ++m)
; #pragma unroll
;                 for (int n = 0; n < 2; ++n) acc[a][b][m][n] = (f32x4){0.f, 0.f, 0.f, 0.f};
;     ...
;         for (int t = 0; t < nt; t += 2) {
;             const bool last = (t == nt - 2);
;             const char* a1 = cA + (size_t)(t + 1) * kstep;
;             const char* a2 = last ? nA : cA + (size_t)(t + 2) * kstep; const char* b2 = last ? nB : cB + (size_t)(t + 2) * kstep;
;             const char* a3 = a2 + kstep; const char* b3 = b2 + kstep;
;             if constexpr (SP2) {
;             PG8_LDB(B0, 0, 0); PG8_LDB(B1, 0, 1); PG8_SCHED; PG8_LDA(At, 0, 0); PG8_STAGE(PG8_SA(1, 1), a1 + hstep, voffA);
;             PG8_WAIT_V(8); PG8_WAIT_L(0); PG8_BAR; PG8_MMA(0, 0, At, B0); PG8_MMA(0, 1, At, B1); PG8_BAR; PG8_SCHED;
;             PG8_LDA(At, 0, 1); PG8_STAGE(PG8_SB(0, 0), b2, voffB); PG8_STAGE(PG8_SB(0, 1), b2 + hstep, voffB); PG8_STAGE(PG8_SA(0, 0), a2, voffA);
.LBB0_1065:
	s_add_u32 s36, s36, 0x40080
	s_addc_u32 s37, s37, 0
	s_add_u32 s9, s38, 0x100
	s_addc_u32 s11, s39, 0
	s_mov_b32 s17, -2
	s_add_u32 s38, s36, 0xfffc0080
	s_addc_u32 s39, s37, -1
	s_add_i32 s72, 0, 0x10000
	s_cmp_eq_u32 s17, 12
	s_cselect_b32 s41, s13, s39
	s_cselect_b32 s40, s12, s38
	s_cselect_b32 s39, s15, s11
	s_cselect_b32 s38, s14, s9
	s_add_i32 s74, 0, 0x14000
	v_add_u32_e32 v154, s72, v144
	v_add_u32_e32 v170, s74, v144
	ds_read_b128 v[138:141], v154
	ds_read_b128 v[146:149], v154 offset:1024
	ds_read_b128 v[150:153], v154 offset:2048
	ds_read_b128 v[154:157], v154 offset:3072
	ds_read_b128 v[158:161], v170
	ds_read_b128 v[162:165], v170 offset:1024
	ds_read_b128 v[166:169], v170 offset:2048
	ds_read_b128 v[170:173], v170 offset:3072
	v_lshl_add_u64 v[190:191], s[36:37], 0, v[134:135]
	s_add_i32 m0, s19, 0xc000
	ds_read_b128 v[174:177], v145
	ds_read_b128 v[178:181], v145 offset:1024
	ds_read_b128 v[182:185], v145 offset:2048
	ds_read_b128 v[186:189], v145 offset:3072
	ds_read_b128 v[208:211], v145 offset:4096
	ds_read_b128 v[212:215], v145 offset:5120
	ds_read_b128 v[216:219], v145 offset:6144
	ds_read_b128 v[220:223], v145 offset:7168
	global_load_lds_dwordx4 v[190:191], off
	v_lshl_add_u64 v[190:191], s[36:37], 0, v[136:137]
	s_add_i32 m0, s19, 0xe000
	s_nop 0
	global_load_lds_dwordx4 v[190:191], off
	s_waitcnt vmcnt(8)
	s_waitcnt lgkmcnt(0)
	s_barrier
	s_setprio 1
	s_waitcnt lgkmcnt(0)
	v_mfma_f32_16x16x32_bf16 v[124:127], v[138:141], v[174:177], 0
	v_mfma_f32_16x16x32_bf16 v[116:119], v[150:153], v[174:177], 0
	v_mfma_f32_16x16x32_bf16 v[108:111], v[138:141], v[182:185], 0
	v_mfma_f32_16x16x32_bf16 v[100:103], v[150:153], v[182:185], 0
	v_mfma_f32_16x16x32_bf16 v[92:95], v[138:141], v[208:211], 0
	v_mfma_f32_16x16x32_bf16 v[84:87], v[150:153], v[208:211], 0
	v_mfma_f32_16x16x32_bf16 v[76:79], v[138:141], v[216:219], 0
	v_mfma_f32_16x16x32_bf16 v[68:71], v[150:153], v[216:219], 0
	v_mfma_f32_16x16x32_bf16 v[124:127], v[146:149], v[178:181], v[124:127]
	v_mfma_f32_16x16x32_bf16 v[116:119], v[154:157], v[178:181], v[116:119]
	v_mfma_f32_16x16x32_bf16 v[108:111], v[146:149], v[186:189], v[108:111]
	v_mfma_f32_16x16x32_bf16 v[100:103], v[154:157], v[186:189], v[100:103]
	v_mfma_f32_16x16x32_bf16 v[92:95], v[146:149], v[212:215], v[92:95]
	v_mfma_f32_16x16x32_bf16 v[84:87], v[154:157], v[212:215], v[84:87]
	v_mfma_f32_16x16x32_bf16 v[76:79], v[146:149], v[220:223], v[76:79]
	v_mfma_f32_16x16x32_bf16 v[68:71], v[154:157], v[220:223], v[68:71]
	s_setprio 0
	s_setprio 1
	v_mfma_f32_16x16x32_bf16 v[120:123], v[158:161], v[174:177], 0
	v_mfma_f32_16x16x32_bf16 v[112:115], v[166:169], v[174:177], 0
	v_mfma_f32_16x16x32_bf16 v[104:107], v[158:161], v[182:185], 0
	v_mfma_f32_16x16x32_bf16 v[96:99], v[166:169], v[182:185], 0
	v_mfma_f32_16x16x32_bf16 v[88:91], v[158:161], v[208:211], 0
	v_mfma_f32_16x16x32_bf16 v[80:83], v[166:169], v[208:211], 0
	v_mfma_f32_16x16x32_bf16 v[72:75], v[158:161], v[216:219], 0
	v_mfma_f32_16x16x32_bf16 v[64:67], v[166:169], v[216:219], 0
	v_mfma_f32_16x16x32_bf16 v[120:123], v[162:165], v[178:181], v[120:123]
	v_mfma_f32_16x16x32_bf16 v[112:115], v[170:173], v[178:181], v[112:115]
	v_mfma_f32_16x16x32_bf16 v[104:107], v[162:165], v[186:189], v[104:107]
	v_mfma_f32_16x16x32_bf16 v[96:99], v[170:173], v[186:189], v[96:99]
	v_mfma_f32_16x16x32_bf16 v[88:91], v[162:165], v[212:215], v[88:91]
	v_mfma_f32_16x16x32_bf16 v[80:83], v[170:173], v[212:215], v[80:83]
	v_mfma_f32_16x16x32_bf16 v[72:75], v[162:165], v[220:223], v[72:75]
	v_mfma_f32_16x16x32_bf16 v[64:67], v[170:173], v[220:223], v[64:67]
	s_setprio 0
	s_barrier
	s_add_i32 s72, s72, s47
	v_lshl_add_u64 v[190:191], s[38:39], 0, v[194:195]
	s_mov_b32 m0, s72
	ds_read_b128 v[174:177], v145 offset:16384
	ds_read_b128 v[178:181], v145 offset:17408
	ds_read_b128 v[182:185], v145 offset:18432
	ds_read_b128 v[186:189], v145 offset:19456
	ds_read_b128 v[208:211], v145 offset:20480
	ds_read_b128 v[212:215], v145 offset:21504
	ds_read_b128 v[216:219], v145 offset:22528
	ds_read_b128 v[220:223], v145 offset:23552
	global_load_lds_dwordx4 v[190:191], off
	s_add_i32 m0, s72, 0x2000
	s_add_u32 s72, s38, 0x40000
	v_lshl_add_u64 v[226:227], s[38:39], 0, v[128:129]
	s_addc_u32 s73, s39, 0
	s_add_i32 s74, s74, s47
	global_load_lds_dwordx4 v[226:227], off
	v_lshl_add_u64 v[228:229], s[72:73], 0, v[194:195]
	s_mov_b32 m0, s74
	v_lshl_add_u64 v[230:231], s[40:41], 0, v[130:131]
	global_load_lds_dwordx4 v[228:229], off
	v_lshl_add_u64 v[228:229], s[72:73], 0, v[128:129]
	s_add_i32 m0, s74, 0x2000
	s_nop 0
	global_load_lds_dwordx4 v[228:229], off
	v_lshl_add_u64 v[228:229], s[40:41], 0, v[132:133]
	s_mov_b32 m0, s19
	s_nop 0
	global_load_lds_dwordx4 v[228:229], off
	s_mov_b32 m0, s58
	s_nop 0
	global_load_lds_dwordx4 v[230:231], off
	s_waitcnt vmcnt(8)
	s_waitcnt lgkmcnt(0)
	s_barrier
; #define PG8_STAGE(bufoff, gbase, voff) do { _Pragma("unroll") for (int _i = 0; _i < 2; ++_i) \
;         __builtin_amdgcn_global_load_lds((const unsigned*)((const char*)(gbase) + (voff)[_i]), (LAS unsigned*)(lds + (bufoff) + ldsw + _i * 8192), 16, 0, 0); } while (0)
; #define PG8_LDA(dst, b, h) do { _Pragma("unroll") for (int m = 0; m < 4; ++m) _Pragma("unroll") for (int k = 0; k < 2; ++k) dst[m][k] = *(const LAS bf16x8*)(lds + PG8_SA(b, h) + aoff + m * 2048 + k * 1024); } while (0)
; #define PG8_LDB(dst, b, h) do { _Pragma("unroll") for (int n = 0; n < 2; ++n) _Pragma("unroll") for (int k = 0; k < 2; ++k) dst[n][k] = *(const LAS bf16x8*)(lds + PG8_SB(b, h) + boff + n * 2048 + k * 1024); } while (0)
; #define PG8_MMA(ai, bj, At, Bt) do { __builtin_amdgcn_s_setprio(1); _Pragma("unroll") for (int m = 0; m < 4; ++m) _Pragma("unroll") for (int n = 0; n < 2; ++n) _Pragma("unroll") for (int k = 0; k < 2; ++k) \
;         acc[ai][bj][m][n] = __builtin_amdgcn_mfma_f32_16x16x32_bf16(Bt[n][k], At[m][k], acc[ai][bj][m][n], 0, 0, 0); __builtin_amdgcn_s_setprio(0); } while (0)
; #define PG8_WAIT_V(n) asm volatile("s_waitcnt vmcnt(" #n ")" ::: "memory")
; #define PG8_WAIT_L(n) asm volatile("s_waitcnt lgkmcnt(" #n ")" ::: "memory")
; #define PG8_BAR __builtin_amdgcn_s_barrier()
; #define PG8_SCHED __builtin_amdgcn_sched_barrier(0)
; template <class Epi, class Sched, bool ALIGN_EPI = true, bool SP2 = true>
; __device__ __forceinline__ void gemm_phase(LAS unsigned char* lds, const int K, const Sched& S, const Epi& E) {
;     ...
;             PG8_WAIT_V(8); PG8_WAIT_L(0); PG8_BAR; PG8_MMA(1, 0, At, B0); PG8_MMA(1, 1, At, B1); PG8_BAR; PG8_SCHED;
;             PG8_LDB(B0, 1, 0); PG8_LDB(B1, 1, 1); PG8_SCHED; PG8_LDA(At, 1, 0); PG8_STAGE(PG8_SA(0, 1), a2 + hstep, voffA);
;             PG8_WAIT_V(8); PG8_WAIT_L(0); PG8_BAR; PG8_MMA(0, 0, At, B0); PG8_MMA(0, 1, At, B1); PG8_BAR; PG8_SCHED;
	s_setprio 1
	s_waitcnt lgkmcnt(0)
	v_mfma_f32_16x16x32_bf16 v[60:63], v[138:141], v[174:177], 0
	v_mfma_f32_16x16x32_bf16 v[52:55], v[150:153], v[174:177], 0
	v_mfma_f32_16x16x32_bf16 v[44:47], v[138:141], v[182:185], 0
	v_mfma_f32_16x16x32_bf16 v[36:39], v[150:153], v[182:185], 0
	v_mfma_f32_16x16x32_bf16 v[28:31], v[138:141], v[208:211], 0
	v_mfma_f32_16x16x32_bf16 v[20:23], v[150:153], v[208:211], 0
	v_mfma_f32_16x16x32_bf16 v[12:15], v[138:141], v[216:219], 0
	v_mfma_f32_16x16x32_bf16 v[4:7], v[150:153], v[216:219], 0
	v_mfma_f32_16x16x32_bf16 v[60:63], v[146:149], v[178:181], v[60:63]
	v_mfma_f32_16x16x32_bf16 v[52:55], v[154:157], v[178:181], v[52:55]
	v_mfma_f32_16x16x32_bf16 v[44:47], v[146:149], v[186:189], v[44:47]
	v_mfma_f32_16x16x32_bf16 v[36:39], v[154:157], v[186:189], v[36:39]
	v_mfma_f32_16x16x32_bf16 v[28:31], v[146:149], v[212:215], v[28:31]
	v_mfma_f32_16x16x32_bf16 v[20:23], v[154:157], v[212:215], v[20:23]
	v_mfma_f32_16x16x32_bf16 v[12:15], v[146:149], v[220:223], v[12:15]
	v_mfma_f32_16x16x32_bf16 v[4:7], v[154:157], v[220:223], v[4:7]
	s_setprio 0
	s_setprio 1
	v_mfma_f32_16x16x32_bf16 v[56:59], v[158:161], v[174:177], 0
	v_mfma_f32_16x16x32_bf16 v[48:51], v[166:169], v[174:177], 0
	v_mfma_f32_16x16x32_bf16 v[40:43], v[158:161], v[182:185], 0
	v_mfma_f32_16x16x32_bf16 v[32:35], v[166:169], v[182:185], 0
	v_mfma_f32_16x16x32_bf16 v[24:27], v[158:161], v[208:211], 0
	v_mfma_f32_16x16x32_bf16 v[16:19], v[166:169], v[208:211], 0
	v_mfma_f32_16x16x32_bf16 v[8:11], v[158:161], v[216:219], 0
	v_mfma_f32_16x16x32_bf16 v[0:3], v[166:169], v[216:219], 0
	v_mfma_f32_16x16x32_bf16 v[56:59], v[162:165], v[178:181], v[56:59]
	v_mfma_f32_16x16x32_bf16 v[48:51], v[170:173], v[178:181], v[48:51]
	v_mfma_f32_16x16x32_bf16 v[40:43], v[162:165], v[186:189], v[40:43]
	v_mfma_f32_16x16x32_bf16 v[32:35], v[170:173], v[186:189], v[32:35]
	v_mfma_f32_16x16x32_bf16 v[24:27], v[162:165], v[212:215], v[24:27]
	v_mfma_f32_16x16x32_bf16 v[16:19], v[170:173], v[212:215], v[16:19]
	v_mfma_f32_16x16x32_bf16 v[8:11], v[162:165], v[220:223], v[8:11]
	v_mfma_f32_16x16x32_bf16 v[0:3], v[170:173], v[220:223], v[0:3]
	s_setprio 0
	s_barrier
	s_add_i32 s72, 0, 0x18000
	s_add_i32 s73, 0, 0x1c000
	v_add_u32_e32 v154, s72, v144
	v_add_u32_e32 v170, s73, v144
	ds_read_b128 v[138:141], v154
	ds_read_b128 v[146:149], v154 offset:1024
	ds_read_b128 v[150:153], v154 offset:2048
	ds_read_b128 v[154:157], v154 offset:3072
	ds_read_b128 v[158:161], v170
	ds_read_b128 v[162:165], v170 offset:1024
	ds_read_b128 v[166:169], v170 offset:2048
	ds_read_b128 v[170:173], v170 offset:3072
	s_add_u32 s40, s40, 0x40000
	s_addc_u32 s41, s41, 0
	s_mov_b32 m0, s59
	v_lshl_add_u64 v[232:233], s[40:41], 0, v[132:133]
	ds_read_b128 v[174:177], v145 offset:32768
	ds_read_b128 v[178:181], v145 offset:33792
	ds_read_b128 v[182:185], v145 offset:34816
	ds_read_b128 v[186:189], v145 offset:35840
	ds_read_b128 v[208:211], v145 offset:36864
	ds_read_b128 v[212:215], v145 offset:37888
	ds_read_b128 v[216:219], v145 offset:38912
	ds_read_b128 v[220:223], v145 offset:39936
	global_load_lds_dwordx4 v[232:233], off
	v_lshl_add_u64 v[232:233], s[40:41], 0, v[130:131]
	s_mov_b32 m0, s66
	s_nop 0
	global_load_lds_dwordx4 v[232:233], off
	s_waitcnt vmcnt(8)
	s_waitcnt lgkmcnt(0)
	s_barrier
	s_setprio 1
	s_waitcnt lgkmcnt(0)
	v_mfma_f32_16x16x32_bf16 v[124:127], v[138:141], v[174:177], v[124:127]
	v_mfma_f32_16x16x32_bf16 v[116:119], v[150:153], v[174:177], v[116:119]
	v_mfma_f32_16x16x32_bf16 v[108:111], v[138:141], v[182:185], v[108:111]
	v_mfma_f32_16x16x32_bf16 v[100:103], v[150:153], v[182:185], v[100:103]
	v_mfma_f32_16x16x32_bf16 v[92:95], v[138:141], v[208:211], v[92:95]
	v_mfma_f32_16x16x32_bf16 v[84:87], v[150:153], v[208:211], v[84:87]
	v_mfma_f32_16x16x32_bf16 v[76:79], v[138:141], v[216:219], v[76:79]
	v_mfma_f32_16x16x32_bf16 v[68:71], v[150:153], v[216:219], v[68:71]
	v_mfma_f32_16x16x32_bf16 v[124:127], v[146:149], v[178:181], v[124:127]
	v_mfma_f32_16x16x32_bf16 v[116:119], v[154:157], v[178:181], v[116:119]
	v_mfma_f32_16x16x32_bf16 v[108:111], v[146:149], v[186:189], v[108:111]
	v_mfma_f32_16x16x32_bf16 v[100:103], v[154:157], v[186:189], v[100:103]
	v_mfma_f32_16x16x32_bf16 v[92:95], v[146:149], v[212:215], v[92:95]
	v_mfma_f32_16x16x32_bf16 v[84:87], v[154:157], v[212:215], v[84:87]
	v_mfma_f32_16x16x32_bf16 v[76:79], v[146:149], v[220:223], v[76:79]
	v_mfma_f32_16x16x32_bf16 v[68:71], v[154:157], v[220:223], v[68:71]
	s_setprio 0
	s_setprio 1
	v_mfma_f32_16x16x32_bf16 v[120:123], v[158:161], v[174:177], v[120:123]
	v_mfma_f32_16x16x32_bf16 v[112:115], v[166:169], v[174:177], v[112:115]
	v_mfma_f32_16x16x32_bf16 v[104:107], v[158:161], v[182:185], v[104:107]
	v_mfma_f32_16x16x32_bf16 v[96:99], v[166:169], v[182:185], v[96:99]
	v_mfma_f32_16x16x32_bf16 v[88:91], v[158:161], v[208:211], v[88:91]
	v_mfma_f32_16x16x32_bf16 v[80:83], v[166:169], v[208:211], v[80:83]
	v_mfma_f32_16x16x32_bf16 v[72:75], v[158:161], v[216:219], v[72:75]
	v_mfma_f32_16x16x32_bf16 v[64:67], v[166:169], v[216:219], v[64:67]
	v_mfma_f32_16x16x32_bf16 v[120:123], v[162:165], v[178:181], v[120:123]
	v_mfma_f32_16x16x32_bf16 v[112:115], v[170:173], v[178:181], v[112:115]
	v_mfma_f32_16x16x32_bf16 v[104:107], v[162:165], v[186:189], v[104:107]
	v_mfma_f32_16x16x32_bf16 v[96:99], v[170:173], v[186:189], v[96:99]
	v_mfma_f32_16x16x32_bf16 v[88:91], v[162:165], v[212:215], v[88:91]
	v_mfma_f32_16x16x32_bf16 v[80:83], v[170:173], v[212:215], v[80:83]
	v_mfma_f32_16x16x32_bf16 v[72:75], v[162:165], v[220:223], v[72:75]
	v_mfma_f32_16x16x32_bf16 v[64:67], v[170:173], v[220:223], v[64:67]
	s_setprio 0
	s_barrier
; #define PG8_STAGE(bufoff, gbase, voff) do { _Pragma("unroll") for (int _i = 0; _i < 2; ++_i) \
;         __builtin_amdgcn_global_load_lds((const unsigned*)((const char*)(gbase) + (voff)[_i]), (LAS unsigned*)(lds + (bufoff) + ldsw + _i * 8192), 16, 0, 0); } while (0)
; #define PG8_LDA(dst, b, h) do { _Pragma("unroll") for (int m = 0; m < 4; ++m) _Pragma("unroll") for (int k = 0; k < 2; ++k) dst[m][k] = *(const LAS bf16x8*)(lds + PG8_SA(b, h) + aoff + m * 2048 + k * 1024); } while (0)
; #define PG8_MMA(ai, bj, At, Bt) do { __builtin_amdgcn_s_setprio(1); _Pragma("unroll") for (int m = 0; m < 4; ++m) _Pragma("unroll") for (int n = 0; n < 2; ++n) _Pragma("unroll") for (int k = 0; k < 2; ++k) \
;         acc[ai][bj][m][n] = __builtin_amdgcn_mfma_f32_16x16x32_bf16(Bt[n][k], At[m][k], acc[ai][bj][m][n], 0, 0, 0); __builtin_amdgcn_s_setprio(0); } while (0)
; #define PG8_WAIT_V(n) asm volatile("s_waitcnt vmcnt(" #n ")" ::: "memory")
; #define PG8_WAIT_L(n) asm volatile("s_waitcnt lgkmcnt(" #n ")" ::: "memory")
; #define PG8_BAR __builtin_amdgcn_s_barrier()
; #define PG8_SCHED __builtin_amdgcn_sched_barrier(0)
; template <class Epi, class Sched, bool ALIGN_EPI = true, bool SP2 = true>
; __device__ __forceinline__ void gemm_phase(LAS unsigned char* lds, const int K, const Sched& S, const Epi& E) {
;     ...
;             PG8_LDA(At, 1, 1); PG8_STAGE(PG8_SB(1, 0), b3, voffB); PG8_STAGE(PG8_SB(1, 1), b3 + hstep, voffB); PG8_STAGE(PG8_SA(1, 0), a3, voffA);
;             PG8_WAIT_V(8); PG8_WAIT_L(0); PG8_BAR; PG8_MMA(1, 0, At, B0); PG8_MMA(1, 1, At, B1); PG8_BAR; PG8_SCHED;
	s_add_i32 s40, s72, s47
	v_lshl_add_u64 v[190:191], v[190:191], 0, s[94:95]
	s_mov_b32 m0, s40
	ds_read_b128 v[174:177], v145 offset:49152
	ds_read_b128 v[178:181], v145 offset:50176
	ds_read_b128 v[182:185], v145 offset:51200
	ds_read_b128 v[186:189], v145 offset:52224
	ds_read_b128 v[208:211], v145 offset:53248
	ds_read_b128 v[212:215], v145 offset:54272
	ds_read_b128 v[216:219], v145 offset:55296
	ds_read_b128 v[220:223], v145 offset:56320
	global_load_lds_dwordx4 v[190:191], off
	s_add_i32 m0, s40, 0x2000
	s_add_u32 s38, s38, 0x40080
	v_lshl_add_u64 v[190:191], v[226:227], 0, s[94:95]
	s_addc_u32 s39, s39, 0
	s_add_i32 s40, s73, s47
	global_load_lds_dwordx4 v[190:191], off
	v_lshl_add_u64 v[190:191], s[38:39], 0, v[194:195]
	s_mov_b32 m0, s40
	s_nop 0
	global_load_lds_dwordx4 v[190:191], off
	v_lshl_add_u64 v[190:191], s[38:39], 0, v[128:129]
	s_add_i32 m0, s40, 0x2000
	s_nop 0
	global_load_lds_dwordx4 v[190:191], off
	v_lshl_add_u64 v[190:191], v[228:229], 0, s[94:95]
	s_mov_b32 m0, s69
	s_nop 0
	global_load_lds_dwordx4 v[190:191], off
	v_lshl_add_u64 v[190:191], v[230:231], 0, s[94:95]
	s_mov_b32 m0, s70
	s_nop 0
	global_load_lds_dwordx4 v[190:191], off
	s_waitcnt vmcnt(8)
	s_waitcnt lgkmcnt(0)
	s_barrier
	s_setprio 1
	s_waitcnt lgkmcnt(0)
	v_mfma_f32_16x16x32_bf16 v[60:63], v[138:141], v[174:177], v[60:63]
	v_mfma_f32_16x16x32_bf16 v[52:55], v[150:153], v[174:177], v[52:55]
	v_mfma_f32_16x16x32_bf16 v[44:47], v[138:141], v[182:185], v[44:47]
	v_mfma_f32_16x16x32_bf16 v[36:39], v[150:153], v[182:185], v[36:39]
	v_mfma_f32_16x16x32_bf16 v[28:31], v[138:141], v[208:211], v[28:31]
	v_mfma_f32_16x16x32_bf16 v[20:23], v[150:153], v[208:211], v[20:23]
	v_mfma_f32_16x16x32_bf16 v[12:15], v[138:141], v[216:219], v[12:15]
	v_mfma_f32_16x16x32_bf16 v[4:7], v[150:153], v[216:219], v[4:7]
	v_mfma_f32_16x16x32_bf16 v[60:63], v[146:149], v[178:181], v[60:63]
	v_mfma_f32_16x16x32_bf16 v[52:55], v[154:157], v[178:181], v[52:55]
	v_mfma_f32_16x16x32_bf16 v[44:47], v[146:149], v[186:189], v[44:47]
	v_mfma_f32_16x16x32_bf16 v[36:39], v[154:157], v[186:189], v[36:39]
	v_mfma_f32_16x16x32_bf16 v[28:31], v[146:149], v[212:215], v[28:31]
	v_mfma_f32_16x16x32_bf16 v[20:23], v[154:157], v[212:215], v[20:23]
	v_mfma_f32_16x16x32_bf16 v[12:15], v[146:149], v[220:223], v[12:15]
	v_mfma_f32_16x16x32_bf16 v[4:7], v[154:157], v[220:223], v[4:7]
	s_setprio 0
	s_setprio 1
	v_mfma_f32_16x16x32_bf16 v[56:59], v[158:161], v[174:177], v[56:59]
	v_mfma_f32_16x16x32_bf16 v[48:51], v[166:169], v[174:177], v[48:51]
	v_mfma_f32_16x16x32_bf16 v[40:43], v[158:161], v[182:185], v[40:43]
	v_mfma_f32_16x16x32_bf16 v[32:35], v[166:169], v[182:185], v[32:35]
	v_mfma_f32_16x16x32_bf16 v[24:27], v[158:161], v[208:211], v[24:27]
	v_mfma_f32_16x16x32_bf16 v[16:19], v[166:169], v[208:211], v[16:19]
	v_mfma_f32_16x16x32_bf16 v[8:11], v[158:161], v[216:219], v[8:11]
	v_mfma_f32_16x16x32_bf16 v[0:3], v[166:169], v[216:219], v[0:3]
	v_mfma_f32_16x16x32_bf16 v[56:59], v[162:165], v[178:181], v[56:59]
	v_mfma_f32_16x16x32_bf16 v[48:51], v[170:173], v[178:181], v[48:51]
	v_mfma_f32_16x16x32_bf16 v[40:43], v[162:165], v[186:189], v[40:43]
	v_mfma_f32_16x16x32_bf16 v[32:35], v[170:173], v[186:189], v[32:35]
	v_mfma_f32_16x16x32_bf16 v[24:27], v[162:165], v[212:215], v[24:27]
	v_mfma_f32_16x16x32_bf16 v[16:19], v[170:173], v[212:215], v[16:19]
	v_mfma_f32_16x16x32_bf16 v[8:11], v[162:165], v[220:223], v[8:11]
	v_mfma_f32_16x16x32_bf16 v[0:3], v[170:173], v[220:223], v[0:3]
	s_setprio 0
	s_barrier
	s_add_i32 s17, s17, 2
	s_add_u32 s36, s36, 0x100
	s_addc_u32 s37, s37, 0
	s_add_u32 s9, s9, 0x100
	s_addc_u32 s11, s11, 0
	s_cmp_gt_u32 s17, 13

; #define PG8_STAGE(bufoff, gbase, voff) do { _Pragma("unroll") for (int _i = 0; _i < 2; ++_i) \
;         __builtin_amdgcn_global_load_lds((const unsigned*)((const char*)(gbase) + (voff)[_i]), (LAS unsigned*)(lds + (bufoff) + ldsw + _i * 8192), 16, 0, 0); } while (0)
; #define PG8_LDA(dst, b, h) do { _Pragma("unroll") for (int m = 0; m < 4; ++m) _Pragma("unroll") for (int k = 0; k < 2; ++k) dst[m][k] = *(const LAS bf16x8*)(lds + PG8_SA(b, h) + aoff + m * 2048 + k * 1024); } while (0)
; #define PG8_LDB(dst, b, h) do { _Pragma("unroll") for (int n = 0; n < 2; ++n) _Pragma("unroll") for (int k = 0; k < 2; ++k) dst[n][k] = *(const LAS bf16x8*)(lds + PG8_SB(b, h) + boff + n * 2048 + k * 1024); } while (0)
; #define PG8_MMA(ai, bj, At, Bt) do { __builtin_amdgcn_s_setprio(1); _Pragma("unroll") for (int m = 0; m < 4; ++m) _Pragma("unroll") for (int n = 0; n < 2; ++n) _Pragma("unroll") for (int k = 0; k < 2; ++k) \
;         acc[ai][bj][m][n] = __builtin_amdgcn_mfma_f32_16x16x32_bf16(Bt[n][k], At[m][k], acc[ai][bj][m][n], 0, 0, 0); __builtin_amdgcn_s_setprio(0); } while (0)
; template <class Epi, class Sched, bool ALIGN_EPI = true, bool SP2 = true>
; __device__ __forceinline__ void gemm_phase(LAS unsigned char* lds, const int K, const Sched& S, const Epi& E) {
;     ...
;     f32x4 acc[2][2][4][2];
; #pragma unroll
;     for (int a = 0; a < 2; ++a)
; #pragma unroll
;         for (int b = 0; b < 2; ++b)
; #pragma unroll
;             for (int m = 0; m < 4; ++m)
; #pragma unroll
;                 for (int n = 0; n < 2; ++n) acc[a][b][m][n] = (f32x4){0.f, 0.f, 0.f, 0.f};
;     ...
;         for (int t = 0; t < nt; t += 2) {
;             const bool last = (t == nt - 2);
;             const char* a1 = cA + (size_t)(t + 1) * kstep;
;             const char* a2 = last ? nA : cA + (size_t)(t + 2) * kstep; const char* b2 = last ? nB : cB + (size_t)(t + 2) * kstep;
;             const char* a3 = a2 + kstep; const char* b3 = b2 + kstep;
;             if constexpr (SP2) {
;             PG8_LDB(B0, 0, 0); PG8_LDB(B1, 0, 1); PG8_SCHED; PG8_LDA(At, 0, 0); PG8_STAGE(PG8_SA(1, 1), a1 + hstep, voffA);
;             PG8_WAIT_V(8); PG8_WAIT_L(0); PG8_BAR; PG8_MMA(0, 0, At, B0); PG8_MMA(0, 1, At, B1); PG8_BAR; PG8_SCHED;
;             PG8_LDA(At, 0, 1); PG8_STAGE(PG8_SB(0, 0), b2, voffB); PG8_STAGE(PG8_SB(0, 1), b2 + hstep, voffB); PG8_STAGE(PG8_SA(0, 0), a2, voffA);
.LBB0_1146:
	s_add_i32 s81, s80, -2
	s_add_u32 vcc_lo, s18, 0x100
	s_addc_u32 vcc_hi, s19, 0
	s_mov_b32 s36, 0
	s_add_i32 s78, s36, 2
	s_add_u32 s18, s16, 0x100
	s_addc_u32 s19, s17, 0
	s_add_i32 s79, 0, 0x10000
	s_cmp_eq_u32 s81, s36
	s_cselect_b32 s39, s13, s19
	s_cselect_b32 s38, s12, s18
	s_cselect_b32 s37, s15, vcc_hi
	s_cselect_b32 s36, s14, vcc_lo
	s_add_i32 s20, 0, 0x14000
	v_add_u32_e32 v150, s79, v164
	v_add_u32_e32 v170, s20, v164
	ds_read_b128 v[138:141], v150
	ds_read_b128 v[142:145], v150 offset:1024
	ds_read_b128 v[146:149], v150 offset:2048
	ds_read_b128 v[150:153], v150 offset:3072
	ds_read_b128 v[154:157], v170
	ds_read_b128 v[158:161], v170 offset:1024
	ds_read_b128 v[166:169], v170 offset:2048
	ds_read_b128 v[170:173], v170 offset:3072
	v_lshl_add_u64 v[190:191], s[16:17], 0, v[134:135]
	s_add_i32 m0, s43, 0xc000
	ds_read_b128 v[174:177], v165
	ds_read_b128 v[178:181], v165 offset:1024
	ds_read_b128 v[182:185], v165 offset:2048
	ds_read_b128 v[186:189], v165 offset:3072
	ds_read_b128 v[208:211], v165 offset:4096
	ds_read_b128 v[212:215], v165 offset:5120
	ds_read_b128 v[216:219], v165 offset:6144
	ds_read_b128 v[220:223], v165 offset:7168
	global_load_lds_dwordx4 v[190:191], off
	v_lshl_add_u64 v[190:191], s[16:17], 0, v[136:137]
	s_add_i32 m0, s43, 0xe000
	s_nop 0
	global_load_lds_dwordx4 v[190:191], off
	s_waitcnt vmcnt(8)
	s_waitcnt lgkmcnt(0)
	s_barrier
	s_setprio 1
	s_waitcnt lgkmcnt(0)
	v_mfma_f32_16x16x32_bf16 v[124:127], v[138:141], v[174:177], 0
	v_mfma_f32_16x16x32_bf16 v[120:123], v[146:149], v[174:177], 0
	v_mfma_f32_16x16x32_bf16 v[116:119], v[138:141], v[182:185], 0
	v_mfma_f32_16x16x32_bf16 v[112:115], v[146:149], v[182:185], 0
	v_mfma_f32_16x16x32_bf16 v[104:107], v[138:141], v[208:211], 0
	v_mfma_f32_16x16x32_bf16 v[96:99], v[146:149], v[208:211], 0
	v_mfma_f32_16x16x32_bf16 v[88:91], v[138:141], v[216:219], 0
	v_mfma_f32_16x16x32_bf16 v[80:83], v[146:149], v[216:219], 0
	v_mfma_f32_16x16x32_bf16 v[124:127], v[142:145], v[178:181], v[124:127]
	v_mfma_f32_16x16x32_bf16 v[120:123], v[150:153], v[178:181], v[120:123]
	v_mfma_f32_16x16x32_bf16 v[116:119], v[142:145], v[186:189], v[116:119]
	v_mfma_f32_16x16x32_bf16 v[112:115], v[150:153], v[186:189], v[112:115]
	v_mfma_f32_16x16x32_bf16 v[104:107], v[142:145], v[212:215], v[104:107]
	v_mfma_f32_16x16x32_bf16 v[96:99], v[150:153], v[212:215], v[96:99]
	v_mfma_f32_16x16x32_bf16 v[88:91], v[142:145], v[220:223], v[88:91]
	v_mfma_f32_16x16x32_bf16 v[80:83], v[150:153], v[220:223], v[80:83]
	s_setprio 0
	s_setprio 1
	v_mfma_f32_16x16x32_bf16 v[108:111], v[154:157], v[174:177], 0
	v_mfma_f32_16x16x32_bf16 v[100:103], v[166:169], v[174:177], 0
	v_mfma_f32_16x16x32_bf16 v[92:95], v[154:157], v[182:185], 0
	v_mfma_f32_16x16x32_bf16 v[84:87], v[166:169], v[182:185], 0
	v_mfma_f32_16x16x32_bf16 v[76:79], v[154:157], v[208:211], 0
	v_mfma_f32_16x16x32_bf16 v[72:75], v[166:169], v[208:211], 0
	v_mfma_f32_16x16x32_bf16 v[68:71], v[154:157], v[216:219], 0
	v_mfma_f32_16x16x32_bf16 v[64:67], v[166:169], v[216:219], 0
	v_mfma_f32_16x16x32_bf16 v[108:111], v[158:161], v[178:181], v[108:111]
	v_mfma_f32_16x16x32_bf16 v[100:103], v[170:173], v[178:181], v[100:103]
	v_mfma_f32_16x16x32_bf16 v[92:95], v[158:161], v[186:189], v[92:95]
	v_mfma_f32_16x16x32_bf16 v[84:87], v[170:173], v[186:189], v[84:87]
	v_mfma_f32_16x16x32_bf16 v[76:79], v[158:161], v[212:215], v[76:79]
	v_mfma_f32_16x16x32_bf16 v[72:75], v[170:173], v[212:215], v[72:75]
	v_mfma_f32_16x16x32_bf16 v[68:71], v[158:161], v[220:223], v[68:71]
	v_mfma_f32_16x16x32_bf16 v[64:67], v[170:173], v[220:223], v[64:67]
	s_setprio 0
	s_barrier
	s_add_i32 s16, s79, s42
	v_lshl_add_u64 v[190:191], s[36:37], 0, v[194:195]
	s_mov_b32 m0, s16
	ds_read_b128 v[174:177], v165 offset:16384
	ds_read_b128 v[178:181], v165 offset:17408
	ds_read_b128 v[182:185], v165 offset:18432
	ds_read_b128 v[186:189], v165 offset:19456
	ds_read_b128 v[208:211], v165 offset:20480
	ds_read_b128 v[212:215], v165 offset:21504
	ds_read_b128 v[216:219], v165 offset:22528
	ds_read_b128 v[220:223], v165 offset:23552
	global_load_lds_dwordx4 v[190:191], off
	s_add_i32 m0, s16, 0x2000
	s_add_u32 s16, s36, 0xb0000
	v_lshl_add_u64 v[226:227], s[36:37], 0, v[132:133]
	s_addc_u32 s17, s37, 0
	s_add_i32 s20, s20, s42
	global_load_lds_dwordx4 v[226:227], off
	v_lshl_add_u64 v[228:229], s[16:17], 0, v[194:195]
	s_mov_b32 m0, s20
	v_lshl_add_u64 v[230:231], s[38:39], 0, v[130:131]
	global_load_lds_dwordx4 v[228:229], off
	v_lshl_add_u64 v[228:229], s[16:17], 0, v[132:133]
	s_add_i32 m0, s20, 0x2000
	s_nop 0
	global_load_lds_dwordx4 v[228:229], off
	v_lshl_add_u64 v[228:229], s[38:39], 0, v[128:129]
	s_mov_b32 m0, s43
	s_nop 0
	global_load_lds_dwordx4 v[228:229], off
	s_mov_b32 m0, s47
	s_nop 0
	global_load_lds_dwordx4 v[230:231], off
	s_waitcnt vmcnt(8)
	s_waitcnt lgkmcnt(0)
	s_barrier
; #define PG8_STAGE(bufoff, gbase, voff) do { _Pragma("unroll") for (int _i = 0; _i < 2; ++_i) \
;         __builtin_amdgcn_global_load_lds((const unsigned*)((const char*)(gbase) + (voff)[_i]), (LAS unsigned*)(lds + (bufoff) + ldsw + _i * 8192), 16, 0, 0); } while (0)
; #define PG8_LDA(dst, b, h) do { _Pragma("unroll") for (int m = 0; m < 4; ++m) _Pragma("unroll") for (int k = 0; k < 2; ++k) dst[m][k] = *(const LAS bf16x8*)(lds + PG8_SA(b, h) + aoff + m * 2048 + k * 1024); } while (0)
; #define PG8_LDB(dst, b, h) do { _Pragma("unroll") for (int n = 0; n < 2; ++n) _Pragma("unroll") for (int k = 0; k < 2; ++k) dst[n][k] = *(const LAS bf16x8*)(lds + PG8_SB(b, h) + boff + n * 2048 + k * 1024); } while (0)
; #define PG8_MMA(ai, bj, At, Bt) do { __builtin_amdgcn_s_setprio(1); _Pragma("unroll") for (int m = 0; m < 4; ++m) _Pragma("unroll") for (int n = 0; n < 2; ++n) _Pragma("unroll") for (int k = 0; k < 2; ++k) \
;         acc[ai][bj][m][n] = __builtin_amdgcn_mfma_f32_16x16x32_bf16(Bt[n][k], At[m][k], acc[ai][bj][m][n], 0, 0, 0); __builtin_amdgcn_s_setprio(0); } while (0)
; #define PG8_WAIT_V(n) asm volatile("s_waitcnt vmcnt(" #n ")" ::: "memory")
; #define PG8_WAIT_L(n) asm volatile("s_waitcnt lgkmcnt(" #n ")" ::: "memory")
; #define PG8_BAR __builtin_amdgcn_s_barrier()
; #define PG8_SCHED __builtin_amdgcn_sched_barrier(0)
; template <class Epi, class Sched, bool ALIGN_EPI = true, bool SP2 = true>
; __device__ __forceinline__ void gemm_phase(LAS unsigned char* lds, const int K, const Sched& S, const Epi& E) {
;     ...
;             PG8_WAIT_V(8); PG8_WAIT_L(0); PG8_BAR; PG8_MMA(1, 0, At, B0); PG8_MMA(1, 1, At, B1); PG8_BAR; PG8_SCHED;
;             PG8_LDB(B0, 1, 0); PG8_LDB(B1, 1, 1); PG8_SCHED; PG8_LDA(At, 1, 0); PG8_STAGE(PG8_SA(0, 1), a2 + hstep, voffA);
;             PG8_WAIT_V(8); PG8_WAIT_L(0); PG8_BAR; PG8_MMA(0, 0, At, B0); PG8_MMA(0, 1, At, B1); PG8_BAR; PG8_SCHED;
	s_setprio 1
	s_waitcnt lgkmcnt(0)
	v_mfma_f32_16x16x32_bf16 v[60:63], v[138:141], v[174:177], 0
	v_mfma_f32_16x16x32_bf16 v[56:59], v[146:149], v[174:177], 0
	v_mfma_f32_16x16x32_bf16 v[52:55], v[138:141], v[182:185], 0
	v_mfma_f32_16x16x32_bf16 v[48:51], v[146:149], v[182:185], 0
	v_mfma_f32_16x16x32_bf16 v[40:43], v[138:141], v[208:211], 0
	v_mfma_f32_16x16x32_bf16 v[32:35], v[146:149], v[208:211], 0
	v_mfma_f32_16x16x32_bf16 v[24:27], v[138:141], v[216:219], 0
	v_mfma_f32_16x16x32_bf16 v[16:19], v[146:149], v[216:219], 0
	v_mfma_f32_16x16x32_bf16 v[60:63], v[142:145], v[178:181], v[60:63]
	v_mfma_f32_16x16x32_bf16 v[56:59], v[150:153], v[178:181], v[56:59]
	v_mfma_f32_16x16x32_bf16 v[52:55], v[142:145], v[186:189], v[52:55]
	v_mfma_f32_16x16x32_bf16 v[48:51], v[150:153], v[186:189], v[48:51]
	v_mfma_f32_16x16x32_bf16 v[40:43], v[142:145], v[212:215], v[40:43]
	v_mfma_f32_16x16x32_bf16 v[32:35], v[150:153], v[212:215], v[32:35]
	v_mfma_f32_16x16x32_bf16 v[24:27], v[142:145], v[220:223], v[24:27]
	v_mfma_f32_16x16x32_bf16 v[16:19], v[150:153], v[220:223], v[16:19]
	s_setprio 0
	s_setprio 1
	v_mfma_f32_16x16x32_bf16 v[44:47], v[154:157], v[174:177], 0
	v_mfma_f32_16x16x32_bf16 v[36:39], v[166:169], v[174:177], 0
	v_mfma_f32_16x16x32_bf16 v[28:31], v[154:157], v[182:185], 0
	v_mfma_f32_16x16x32_bf16 v[20:23], v[166:169], v[182:185], 0
	v_mfma_f32_16x16x32_bf16 v[12:15], v[154:157], v[208:211], 0
	v_mfma_f32_16x16x32_bf16 v[8:11], v[166:169], v[208:211], 0
	v_mfma_f32_16x16x32_bf16 v[4:7], v[154:157], v[216:219], 0
	v_mfma_f32_16x16x32_bf16 v[0:3], v[166:169], v[216:219], 0
	v_mfma_f32_16x16x32_bf16 v[44:47], v[158:161], v[178:181], v[44:47]
	v_mfma_f32_16x16x32_bf16 v[36:39], v[170:173], v[178:181], v[36:39]
	v_mfma_f32_16x16x32_bf16 v[28:31], v[158:161], v[186:189], v[28:31]
	v_mfma_f32_16x16x32_bf16 v[20:23], v[170:173], v[186:189], v[20:23]
	v_mfma_f32_16x16x32_bf16 v[12:15], v[158:161], v[212:215], v[12:15]
	v_mfma_f32_16x16x32_bf16 v[8:11], v[170:173], v[212:215], v[8:11]
	v_mfma_f32_16x16x32_bf16 v[4:7], v[158:161], v[220:223], v[4:7]
	v_mfma_f32_16x16x32_bf16 v[0:3], v[170:173], v[220:223], v[0:3]
	s_setprio 0
	s_barrier
	s_add_i32 s20, 0, 0x18000
	s_add_i32 s21, 0, 0x1c000
	v_add_u32_e32 v150, s20, v164
	v_add_u32_e32 v170, s21, v164
	ds_read_b128 v[138:141], v150
	ds_read_b128 v[142:145], v150 offset:1024
	ds_read_b128 v[146:149], v150 offset:2048
	ds_read_b128 v[150:153], v150 offset:3072
	ds_read_b128 v[154:157], v170
	ds_read_b128 v[158:161], v170 offset:1024
	ds_read_b128 v[166:169], v170 offset:2048
	ds_read_b128 v[170:173], v170 offset:3072
	s_add_u32 s16, s38, 0xb0000
	s_addc_u32 s17, s39, 0
	s_mov_b32 m0, s56
	v_lshl_add_u64 v[232:233], s[16:17], 0, v[128:129]
	ds_read_b128 v[174:177], v165 offset:32768
	ds_read_b128 v[178:181], v165 offset:33792
	ds_read_b128 v[182:185], v165 offset:34816
	ds_read_b128 v[186:189], v165 offset:35840
	ds_read_b128 v[208:211], v165 offset:36864
	ds_read_b128 v[212:215], v165 offset:37888
	ds_read_b128 v[216:219], v165 offset:38912
	ds_read_b128 v[220:223], v165 offset:39936
	global_load_lds_dwordx4 v[232:233], off
	v_lshl_add_u64 v[232:233], s[16:17], 0, v[130:131]
	s_mov_b32 m0, s57
	s_nop 0
	global_load_lds_dwordx4 v[232:233], off
	s_waitcnt vmcnt(8)
	s_waitcnt lgkmcnt(0)
	s_barrier
	s_setprio 1
	s_waitcnt lgkmcnt(0)
	v_mfma_f32_16x16x32_bf16 v[124:127], v[138:141], v[174:177], v[124:127]
	v_mfma_f32_16x16x32_bf16 v[120:123], v[146:149], v[174:177], v[120:123]
	v_mfma_f32_16x16x32_bf16 v[116:119], v[138:141], v[182:185], v[116:119]
	v_mfma_f32_16x16x32_bf16 v[112:115], v[146:149], v[182:185], v[112:115]
	v_mfma_f32_16x16x32_bf16 v[104:107], v[138:141], v[208:211], v[104:107]
	v_mfma_f32_16x16x32_bf16 v[96:99], v[146:149], v[208:211], v[96:99]
	v_mfma_f32_16x16x32_bf16 v[88:91], v[138:141], v[216:219], v[88:91]
	v_mfma_f32_16x16x32_bf16 v[80:83], v[146:149], v[216:219], v[80:83]
	v_mfma_f32_16x16x32_bf16 v[124:127], v[142:145], v[178:181], v[124:127]
	v_mfma_f32_16x16x32_bf16 v[120:123], v[150:153], v[178:181], v[120:123]
	v_mfma_f32_16x16x32_bf16 v[116:119], v[142:145], v[186:189], v[116:119]
	v_mfma_f32_16x16x32_bf16 v[112:115], v[150:153], v[186:189], v[112:115]
	v_mfma_f32_16x16x32_bf16 v[104:107], v[142:145], v[212:215], v[104:107]
	v_mfma_f32_16x16x32_bf16 v[96:99], v[150:153], v[212:215], v[96:99]
	v_mfma_f32_16x16x32_bf16 v[88:91], v[142:145], v[220:223], v[88:91]
	v_mfma_f32_16x16x32_bf16 v[80:83], v[150:153], v[220:223], v[80:83]
	s_setprio 0
	s_setprio 1
	v_mfma_f32_16x16x32_bf16 v[108:111], v[154:157], v[174:177], v[108:111]
	v_mfma_f32_16x16x32_bf16 v[100:103], v[166:169], v[174:177], v[100:103]
	v_mfma_f32_16x16x32_bf16 v[92:95], v[154:157], v[182:185], v[92:95]
	v_mfma_f32_16x16x32_bf16 v[84:87], v[166:169], v[182:185], v[84:87]
	v_mfma_f32_16x16x32_bf16 v[76:79], v[154:157], v[208:211], v[76:79]
	v_mfma_f32_16x16x32_bf16 v[72:75], v[166:169], v[208:211], v[72:75]
	v_mfma_f32_16x16x32_bf16 v[68:71], v[154:157], v[216:219], v[68:71]
	v_mfma_f32_16x16x32_bf16 v[64:67], v[166:169], v[216:219], v[64:67]
	v_mfma_f32_16x16x32_bf16 v[108:111], v[158:161], v[178:181], v[108:111]
	v_mfma_f32_16x16x32_bf16 v[100:103], v[170:173], v[178:181], v[100:103]
	v_mfma_f32_16x16x32_bf16 v[92:95], v[158:161], v[186:189], v[92:95]
	v_mfma_f32_16x16x32_bf16 v[84:87], v[170:173], v[186:189], v[84:87]
	v_mfma_f32_16x16x32_bf16 v[76:79], v[158:161], v[212:215], v[76:79]
	v_mfma_f32_16x16x32_bf16 v[72:75], v[170:173], v[212:215], v[72:75]
	v_mfma_f32_16x16x32_bf16 v[68:71], v[158:161], v[220:223], v[68:71]
	v_mfma_f32_16x16x32_bf16 v[64:67], v[170:173], v[220:223], v[64:67]
	s_setprio 0
	s_barrier
; #define PG8_STAGE(bufoff, gbase, voff) do { _Pragma("unroll") for (int _i = 0; _i < 2; ++_i) \
;         __builtin_amdgcn_global_load_lds((const unsigned*)((const char*)(gbase) + (voff)[_i]), (LAS unsigned*)(lds + (bufoff) + ldsw + _i * 8192), 16, 0, 0); } while (0)
; #define PG8_LDA(dst, b, h) do { _Pragma("unroll") for (int m = 0; m < 4; ++m) _Pragma("unroll") for (int k = 0; k < 2; ++k) dst[m][k] = *(const LAS bf16x8*)(lds + PG8_SA(b, h) + aoff + m * 2048 + k * 1024); } while (0)
; #define PG8_MMA(ai, bj, At, Bt) do { __builtin_amdgcn_s_setprio(1); _Pragma("unroll") for (int m = 0; m < 4; ++m) _Pragma("unroll") for (int n = 0; n < 2; ++n) _Pragma("unroll") for (int k = 0; k < 2; ++k) \
;         acc[ai][bj][m][n] = __builtin_amdgcn_mfma_f32_16x16x32_bf16(Bt[n][k], At[m][k], acc[ai][bj][m][n], 0, 0, 0); __builtin_amdgcn_s_setprio(0); } while (0)
; #define PG8_WAIT_V(n) asm volatile("s_waitcnt vmcnt(" #n ")" ::: "memory")
; #define PG8_WAIT_L(n) asm volatile("s_waitcnt lgkmcnt(" #n ")" ::: "memory")
; #define PG8_BAR __builtin_amdgcn_s_barrier()
; #define PG8_SCHED __builtin_amdgcn_sched_barrier(0)
; template <class Epi, class Sched, bool ALIGN_EPI = true, bool SP2 = true>
; __device__ __forceinline__ void gemm_phase(LAS unsigned char* lds, const int K, const Sched& S, const Epi& E) {
;     ...
;             PG8_LDA(At, 1, 1); PG8_STAGE(PG8_SB(1, 0), b3, voffB); PG8_STAGE(PG8_SB(1, 1), b3 + hstep, voffB); PG8_STAGE(PG8_SA(1, 0), a3, voffA);
;             PG8_WAIT_V(8); PG8_WAIT_L(0); PG8_BAR; PG8_MMA(1, 0, At, B0); PG8_MMA(1, 1, At, B1); PG8_BAR; PG8_SCHED;
	s_add_i32 s16, s20, s42
	v_lshl_add_u64 v[190:191], v[190:191], 0, s[94:95]
	s_mov_b32 m0, s16
	ds_read_b128 v[174:177], v165 offset:49152
	ds_read_b128 v[178:181], v165 offset:50176
	ds_read_b128 v[182:185], v165 offset:51200
	ds_read_b128 v[186:189], v165 offset:52224
	ds_read_b128 v[208:211], v165 offset:53248
	ds_read_b128 v[212:215], v165 offset:54272
	ds_read_b128 v[216:219], v165 offset:55296
	ds_read_b128 v[220:223], v165 offset:56320
	global_load_lds_dwordx4 v[190:191], off
	s_add_i32 m0, s16, 0x2000
	s_add_u32 s16, s36, 0xb0080
	v_lshl_add_u64 v[190:191], v[226:227], 0, s[94:95]
	s_addc_u32 s17, s37, 0
	s_add_i32 s20, s21, s42
	global_load_lds_dwordx4 v[190:191], off
	v_lshl_add_u64 v[190:191], s[16:17], 0, v[194:195]
	s_mov_b32 m0, s20
	s_nop 0
	global_load_lds_dwordx4 v[190:191], off
	v_lshl_add_u64 v[190:191], s[16:17], 0, v[132:133]
	s_add_i32 m0, s20, 0x2000
	s_nop 0
	global_load_lds_dwordx4 v[190:191], off
	v_lshl_add_u64 v[190:191], v[228:229], 0, s[94:95]
	s_mov_b32 m0, s68
	s_nop 0
	global_load_lds_dwordx4 v[190:191], off
	v_lshl_add_u64 v[190:191], v[230:231], 0, s[94:95]
	s_mov_b32 m0, s69
	s_nop 0
	global_load_lds_dwordx4 v[190:191], off
	s_waitcnt vmcnt(8)
	s_waitcnt lgkmcnt(0)
	s_barrier
	s_setprio 1
	s_waitcnt lgkmcnt(0)
	v_mfma_f32_16x16x32_bf16 v[60:63], v[138:141], v[174:177], v[60:63]
	v_mfma_f32_16x16x32_bf16 v[56:59], v[146:149], v[174:177], v[56:59]
	v_mfma_f32_16x16x32_bf16 v[52:55], v[138:141], v[182:185], v[52:55]
	v_mfma_f32_16x16x32_bf16 v[48:51], v[146:149], v[182:185], v[48:51]
	v_mfma_f32_16x16x32_bf16 v[40:43], v[138:141], v[208:211], v[40:43]
	v_mfma_f32_16x16x32_bf16 v[32:35], v[146:149], v[208:211], v[32:35]
	v_mfma_f32_16x16x32_bf16 v[24:27], v[138:141], v[216:219], v[24:27]
	v_mfma_f32_16x16x32_bf16 v[16:19], v[146:149], v[216:219], v[16:19]
	v_mfma_f32_16x16x32_bf16 v[60:63], v[142:145], v[178:181], v[60:63]
	v_mfma_f32_16x16x32_bf16 v[56:59], v[150:153], v[178:181], v[56:59]
	v_mfma_f32_16x16x32_bf16 v[52:55], v[142:145], v[186:189], v[52:55]
	v_mfma_f32_16x16x32_bf16 v[48:51], v[150:153], v[186:189], v[48:51]
	v_mfma_f32_16x16x32_bf16 v[40:43], v[142:145], v[212:215], v[40:43]
	v_mfma_f32_16x16x32_bf16 v[32:35], v[150:153], v[212:215], v[32:35]
	v_mfma_f32_16x16x32_bf16 v[24:27], v[142:145], v[220:223], v[24:27]
	v_mfma_f32_16x16x32_bf16 v[16:19], v[150:153], v[220:223], v[16:19]
	s_setprio 0
	s_setprio 1
	v_mfma_f32_16x16x32_bf16 v[44:47], v[154:157], v[174:177], v[44:47]
	v_mfma_f32_16x16x32_bf16 v[36:39], v[166:169], v[174:177], v[36:39]
	v_mfma_f32_16x16x32_bf16 v[28:31], v[154:157], v[182:185], v[28:31]
	v_mfma_f32_16x16x32_bf16 v[20:23], v[166:169], v[182:185], v[20:23]
	v_mfma_f32_16x16x32_bf16 v[12:15], v[154:157], v[208:211], v[12:15]
	v_mfma_f32_16x16x32_bf16 v[8:11], v[166:169], v[208:211], v[8:11]
	v_mfma_f32_16x16x32_bf16 v[4:7], v[154:157], v[216:219], v[4:7]
	v_mfma_f32_16x16x32_bf16 v[0:3], v[166:169], v[216:219], v[0:3]
	v_mfma_f32_16x16x32_bf16 v[44:47], v[158:161], v[178:181], v[44:47]
	v_mfma_f32_16x16x32_bf16 v[36:39], v[170:173], v[178:181], v[36:39]
	v_mfma_f32_16x16x32_bf16 v[28:31], v[158:161], v[186:189], v[28:31]
	v_mfma_f32_16x16x32_bf16 v[20:23], v[170:173], v[186:189], v[20:23]
	v_mfma_f32_16x16x32_bf16 v[12:15], v[158:161], v[212:215], v[12:15]
	v_mfma_f32_16x16x32_bf16 v[8:11], v[170:173], v[212:215], v[8:11]
	v_mfma_f32_16x16x32_bf16 v[4:7], v[158:161], v[220:223], v[4:7]
	v_mfma_f32_16x16x32_bf16 v[0:3], v[170:173], v[220:223], v[0:3]
	s_setprio 0
	s_barrier
	s_add_u32 vcc_lo, vcc_lo, 0x100
	s_addc_u32 vcc_hi, vcc_hi, 0
	s_cmp_ge_i32 s78, s80
	s_mov_b64 s[16:17], s[18:19]
	s_mov_b32 s36, s78
